# GEMM tiles: first K-iteration peeled in front of the loop with C=0 on the first MFMA of every accumulator; the 128 v_mov zeroing the accumulators before each tile dropped
# speedup vs baseline: 1.0096x; 1.0096x over previous
; #define PG8_STAGE(bufoff, gbase, voff) do { _Pragma("unroll") for (int _i = 0; _i < 2; ++_i) \
;         __builtin_amdgcn_global_load_lds((const unsigned*)((const char*)(gbase) + (voff)[_i]), (PG8_LAS unsigned*)(lds + (bufoff) + ldsw + _i * 8192), 16, 0, 0); } while (0)
; #define PG8_LDA(dst, b, h) do { _Pragma("unroll") for (int m = 0; m < 4; ++m) _Pragma("unroll") for (int k = 0; k < 2; ++k) dst[m][k] = *(const PG8_LAS bf16x8*)(lds + PG8_SA(b, h) + aoff + m * 2048 + k * 1024); } while (0)
; #define PG8_LDB(dst, b, h) do { _Pragma("unroll") for (int n = 0; n < 2; ++n) _Pragma("unroll") for (int k = 0; k < 2; ++k) dst[n][k] = *(const PG8_LAS bf16x8*)(lds + PG8_SB(b, h) + boff + n * 2048 + k * 1024); } while (0)
; #define PG8_WAIT_V(n) asm volatile("s_waitcnt vmcnt(" #n ")" ::: "memory")
; #define PG8_WAIT_L(n) asm volatile("s_waitcnt lgkmcnt(" #n ")" ::: "memory")
; #define PG8_BAR __builtin_amdgcn_s_barrier()
; #define PG8_SCHED __builtin_amdgcn_sched_barrier(0)
; template <class Epi, class Sched>
; __device__ __forceinline__ void gemm_phase(PG8_LAS unsigned char* lds, const Gemm g, const Sched& S, const Epi& E) {
;     ...
;         const bool has_next = S.next(ui + 1, nxt);
;         const char* nA = has_next ? (const char*)g.A + (size_t)nxt.pm * tstep : cA; const char* nB = has_next ? (const char*)g.Bt + (size_t)nxt.pn * tstep : cB;
;         for (int t = 0; t < nt; t += 2) {
;             const bool last = (t == nt - 2);
;             const char* a1 = cA + (size_t)(t + 1) * kstep;
;             const char* a2 = last ? nA : cA + (size_t)(t + 2) * kstep; const char* b2 = last ? nB : cB + (size_t)(t + 2) * kstep;
;             const char* a3 = a2 + kstep; const char* b3 = b2 + kstep;
;             if (last && has_next) S.a_ready(nxt);
;             PG8_LDB(B0, 0, 0); PG8_SCHED; PG8_LDA(At, 0, 0); PG8_STAGE(PG8_SA(1, 1), a1 + hstep, voffA);
;             PG8_WAIT_L(8); PG8_BAR; PG8_WAIT_L(0); PG8_MMA(0, 0, At, B0); PG8_BAR; PG8_SCHED;
;             PG8_LDB(B1, 0, 1); PG8_STAGE(PG8_SB(0, 0), b2, voffB);
;             PG8_BAR; PG8_WAIT_L(0); PG8_MMA(0, 1, At, B1); PG8_BAR;
;             PG8_LDA(At, 0, 1); PG8_STAGE(PG8_SA(0, 0), a2, voffA);
;             PG8_BAR; PG8_WAIT_L(0); PG8_MMA(1, 0, At, B0); PG8_BAR; PG8_SCHED;
;             PG8_STAGE(PG8_SB(0, 1), b2 + hstep, voffB);
;             PG8_WAIT_V(6); PG8_BAR; PG8_MMA(1, 1, At, B1); PG8_BAR;
.LBB0_95:
	s_add_u32 s43, s10, 0x100
	s_addc_u32 s44, s11, 0
	s_mov_b32 s45, -2
	s_add_u32 s10, s8, 0x100
	s_addc_u32 s11, s9, 0
	v_add_u32_e32 v154, 0x10000, v139
	ds_read_b128 v[142:145], v154
	ds_read_b128 v[146:149], v154 offset:1024
	ds_read_b128 v[150:153], v154 offset:2048
	ds_read_b128 v[154:157], v154 offset:3072
	s_cmp_eq_u32 s45, 40
	s_cselect_b32 s15, s1, s11
	s_cselect_b32 s14, s0, s10
	s_cselect_b32 s13, s5, s44
	s_cselect_b32 s12, s4, s43
	s_add_i32 m0, s20, 0xc000
	ds_read_b128 v[158:161], v141
	ds_read_b128 v[162:165], v141 offset:1024
	ds_read_b128 v[166:169], v141 offset:2048
	ds_read_b128 v[170:173], v141 offset:3072
	ds_read_b128 v[178:181], v141 offset:4096
	ds_read_b128 v[182:185], v141 offset:5120
	ds_read_b128 v[186:189], v141 offset:6144
	global_load_lds_dwordx4 v134, s[8:9]
	s_add_i32 m0, s20, 0xe000
	ds_read_b128 v[190:193], v141 offset:7168
	global_load_lds_dwordx4 v136, s[8:9]
	s_waitcnt lgkmcnt(8)
	s_barrier
	s_waitcnt lgkmcnt(7)
	v_mfma_f32_16x16x32_bf16 v[124:127], v[142:145], v[158:161], 0
	v_mfma_f32_16x16x32_bf16 v[120:123], v[150:153], v[158:161], 0
	s_waitcnt lgkmcnt(5)
	v_mfma_f32_16x16x32_bf16 v[116:119], v[142:145], v[166:169], 0
	v_mfma_f32_16x16x32_bf16 v[112:115], v[150:153], v[166:169], 0
	s_waitcnt lgkmcnt(3)
	v_mfma_f32_16x16x32_bf16 v[100:103], v[142:145], v[178:181], 0
	v_mfma_f32_16x16x32_bf16 v[96:99], v[150:153], v[178:181], 0
	s_waitcnt lgkmcnt(1)
	v_mfma_f32_16x16x32_bf16 v[84:87], v[142:145], v[186:189], 0
	v_mfma_f32_16x16x32_bf16 v[80:83], v[150:153], v[186:189], 0
	v_mfma_f32_16x16x32_bf16 v[124:127], v[146:149], v[162:165], v[124:127]
	v_mfma_f32_16x16x32_bf16 v[120:123], v[154:157], v[162:165], v[120:123]
	v_mfma_f32_16x16x32_bf16 v[116:119], v[146:149], v[170:173], v[116:119]
	v_mfma_f32_16x16x32_bf16 v[112:115], v[154:157], v[170:173], v[112:115]
	v_mfma_f32_16x16x32_bf16 v[100:103], v[146:149], v[182:185], v[100:103]
	v_mfma_f32_16x16x32_bf16 v[96:99], v[154:157], v[182:185], v[96:99]
	s_waitcnt lgkmcnt(0)
	v_mfma_f32_16x16x32_bf16 v[84:87], v[146:149], v[190:193], v[84:87]
	v_mfma_f32_16x16x32_bf16 v[80:83], v[154:157], v[190:193], v[80:83]
	s_barrier
	s_add_i32 s47, 0, 0x14000
	v_add_u32_e32 v174, 0x14000, v139
	ds_read_b128 v[194:197], v174
	ds_read_b128 v[198:201], v174 offset:1024
	s_add_u32 s98, s12, 0x80
	s_addc_u32 s99, s13, 0
	s_add_i32 m0, s18, 0x10000
	ds_read_b128 v[202:205], v174 offset:2048
	global_load_lds_dwordx4 v176, s[12:13]
	s_add_i32 m0, s18, 0x12000
	ds_read_b128 v[206:209], v174 offset:3072
	global_load_lds_dwordx4 v128, s[12:13]
	s_barrier
	s_waitcnt lgkmcnt(3)
	v_mfma_f32_16x16x32_bf16 v[108:111], v[194:197], v[158:161], 0
	s_waitcnt lgkmcnt(1)
	v_mfma_f32_16x16x32_bf16 v[104:107], v[202:205], v[158:161], 0
	v_mfma_f32_16x16x32_bf16 v[92:95], v[194:197], v[166:169], 0
	v_mfma_f32_16x16x32_bf16 v[88:91], v[202:205], v[166:169], 0
	v_mfma_f32_16x16x32_bf16 v[76:79], v[194:197], v[178:181], 0
	v_mfma_f32_16x16x32_bf16 v[72:75], v[202:205], v[178:181], 0
	v_mfma_f32_16x16x32_bf16 v[68:71], v[194:197], v[186:189], 0
	v_mfma_f32_16x16x32_bf16 v[64:67], v[202:205], v[186:189], 0
	v_mfma_f32_16x16x32_bf16 v[108:111], v[198:201], v[162:165], v[108:111]
	s_waitcnt lgkmcnt(0)
	v_mfma_f32_16x16x32_bf16 v[104:107], v[206:209], v[162:165], v[104:107]
	v_mfma_f32_16x16x32_bf16 v[92:95], v[198:201], v[170:173], v[92:95]
	v_mfma_f32_16x16x32_bf16 v[88:91], v[206:209], v[170:173], v[88:91]
	v_mfma_f32_16x16x32_bf16 v[76:79], v[198:201], v[182:185], v[76:79]
	v_mfma_f32_16x16x32_bf16 v[72:75], v[206:209], v[182:185], v[72:75]
	v_mfma_f32_16x16x32_bf16 v[68:71], v[198:201], v[190:193], v[68:71]
	v_mfma_f32_16x16x32_bf16 v[64:67], v[206:209], v[190:193], v[64:67]
	s_mov_b32 m0, s20
	s_add_u32 s100, s14, 0x80
	s_addc_u32 s101, s15, 0
	s_barrier
	ds_read_b128 v[158:161], v141 offset:16384
	ds_read_b128 v[162:165], v141 offset:17408
	ds_read_b128 v[166:169], v141 offset:18432
	ds_read_b128 v[170:173], v141 offset:19456
	ds_read_b128 v[178:181], v141 offset:20480
	ds_read_b128 v[182:185], v141 offset:21504
	ds_read_b128 v[186:189], v141 offset:22528
	global_load_lds_dwordx4 v132, s[14:15]
	s_mov_b32 m0, s21
	ds_read_b128 v[190:193], v141 offset:23552
	global_load_lds_dwordx4 v130, s[14:15]
	s_barrier
	s_waitcnt lgkmcnt(7)
	v_mfma_f32_16x16x32_bf16 v[60:63], v[142:145], v[158:161], 0
	v_mfma_f32_16x16x32_bf16 v[56:59], v[150:153], v[158:161], 0
	s_waitcnt lgkmcnt(5)
	v_mfma_f32_16x16x32_bf16 v[52:55], v[142:145], v[166:169], 0
	v_mfma_f32_16x16x32_bf16 v[48:51], v[150:153], v[166:169], 0
	s_waitcnt lgkmcnt(3)
	v_mfma_f32_16x16x32_bf16 v[36:39], v[142:145], v[178:181], 0
	v_mfma_f32_16x16x32_bf16 v[32:35], v[150:153], v[178:181], 0
	s_waitcnt lgkmcnt(1)
	v_mfma_f32_16x16x32_bf16 v[20:23], v[142:145], v[186:189], 0
	v_mfma_f32_16x16x32_bf16 v[16:19], v[150:153], v[186:189], 0
	v_mfma_f32_16x16x32_bf16 v[60:63], v[146:149], v[162:165], v[60:63]
	v_mfma_f32_16x16x32_bf16 v[56:59], v[154:157], v[162:165], v[56:59]
	v_mfma_f32_16x16x32_bf16 v[52:55], v[146:149], v[170:173], v[52:55]
	v_mfma_f32_16x16x32_bf16 v[48:51], v[154:157], v[170:173], v[48:51]
	v_mfma_f32_16x16x32_bf16 v[36:39], v[146:149], v[182:185], v[36:39]
	v_mfma_f32_16x16x32_bf16 v[32:35], v[154:157], v[182:185], v[32:35]
	s_waitcnt lgkmcnt(0)
	v_mfma_f32_16x16x32_bf16 v[20:23], v[146:149], v[190:193], v[20:23]
	v_mfma_f32_16x16x32_bf16 v[16:19], v[154:157], v[190:193], v[16:19]
	s_barrier
	s_add_u32 s8, s12, 0xb0000
	s_addc_u32 s9, s13, 0
	s_add_i32 m0, s18, 0x14000
	s_nop 0
	global_load_lds_dwordx4 v176, s[8:9]
	s_add_i32 m0, s18, 0x16000
	s_nop 0
	global_load_lds_dwordx4 v128, s[8:9]
	s_waitcnt vmcnt(6)
	s_barrier
; #define PG8_STAGE(bufoff, gbase, voff) do { _Pragma("unroll") for (int _i = 0; _i < 2; ++_i) \
;         __builtin_amdgcn_global_load_lds((const unsigned*)((const char*)(gbase) + (voff)[_i]), (PG8_LAS unsigned*)(lds + (bufoff) + ldsw + _i * 8192), 16, 0, 0); } while (0)
; #define PG8_LDA(dst, b, h) do { _Pragma("unroll") for (int m = 0; m < 4; ++m) _Pragma("unroll") for (int k = 0; k < 2; ++k) dst[m][k] = *(const PG8_LAS bf16x8*)(lds + PG8_SA(b, h) + aoff + m * 2048 + k * 1024); } while (0)
; #define PG8_LDB(dst, b, h) do { _Pragma("unroll") for (int n = 0; n < 2; ++n) _Pragma("unroll") for (int k = 0; k < 2; ++k) dst[n][k] = *(const PG8_LAS bf16x8*)(lds + PG8_SB(b, h) + boff + n * 2048 + k * 1024); } while (0)
; #define PG8_MMA(ai, bj, At, Bt) do { __builtin_amdgcn_s_setprio(1); _Pragma("unroll") for (int m = 0; m < 4; ++m) _Pragma("unroll") for (int n = 0; n < 2; ++n) _Pragma("unroll") for (int k = 0; k < 2; ++k) \
;         acc[ai][bj][m][n] = __builtin_amdgcn_mfma_f32_16x16x32_bf16(Bt[n][k], At[m][k], acc[ai][bj][m][n], 0, 0, 0); __builtin_amdgcn_s_setprio(0); } while (0)
; #define PG8_WAIT_V(n) asm volatile("s_waitcnt vmcnt(" #n ")" ::: "memory")
; #define PG8_WAIT_L(n) asm volatile("s_waitcnt lgkmcnt(" #n ")" ::: "memory")
; #define PG8_BAR __builtin_amdgcn_s_barrier()
; #define PG8_SCHED __builtin_amdgcn_sched_barrier(0)
; template <class Epi, class Sched>
; __device__ __forceinline__ void gemm_phase(PG8_LAS unsigned char* lds, const Gemm g, const Sched& S, const Epi& E) {
;     ...
;             PG8_WAIT_V(6); PG8_BAR; PG8_MMA(1, 1, At, B1); PG8_BAR;
;             PG8_LDB(B0, 1, 0); PG8_SCHED; PG8_LDA(At, 1, 0); PG8_STAGE(PG8_SA(0, 1), a2 + hstep, voffA);
;             PG8_WAIT_L(8); PG8_BAR; PG8_WAIT_L(0); PG8_MMA(0, 0, At, B0); PG8_BAR; PG8_SCHED;
;             PG8_LDB(B1, 1, 1); PG8_STAGE(PG8_SB(1, 0), b3, voffB);
;             PG8_BAR; PG8_WAIT_L(0); PG8_MMA(0, 1, At, B1); PG8_BAR;
	v_mfma_f32_16x16x32_bf16 v[44:47], v[194:197], v[158:161], 0
	v_mfma_f32_16x16x32_bf16 v[40:43], v[202:205], v[158:161], 0
	v_mfma_f32_16x16x32_bf16 v[28:31], v[194:197], v[166:169], 0
	v_mfma_f32_16x16x32_bf16 v[24:27], v[202:205], v[166:169], 0
	v_mfma_f32_16x16x32_bf16 v[12:15], v[194:197], v[178:181], 0
	v_mfma_f32_16x16x32_bf16 v[8:11], v[202:205], v[178:181], 0
	v_mfma_f32_16x16x32_bf16 v[4:7], v[194:197], v[186:189], 0
	v_mfma_f32_16x16x32_bf16 v[0:3], v[202:205], v[186:189], 0
	v_mfma_f32_16x16x32_bf16 v[44:47], v[198:201], v[162:165], v[44:47]
	v_mfma_f32_16x16x32_bf16 v[40:43], v[206:209], v[162:165], v[40:43]
	v_mfma_f32_16x16x32_bf16 v[28:31], v[198:201], v[170:173], v[28:31]
	v_mfma_f32_16x16x32_bf16 v[24:27], v[206:209], v[170:173], v[24:27]
	v_mfma_f32_16x16x32_bf16 v[12:15], v[198:201], v[182:185], v[12:15]
	v_mfma_f32_16x16x32_bf16 v[8:11], v[206:209], v[182:185], v[8:11]
	v_mfma_f32_16x16x32_bf16 v[4:7], v[198:201], v[190:193], v[4:7]
	v_mfma_f32_16x16x32_bf16 v[0:3], v[206:209], v[190:193], v[0:3]
	s_add_i32 s46, 0, 0x18000
	v_add_u32_e32 v154, 0x18000, v139
	s_barrier
	ds_read_b128 v[142:145], v154
	ds_read_b128 v[146:149], v154 offset:1024
	ds_read_b128 v[150:153], v154 offset:2048
	ds_read_b128 v[154:157], v154 offset:3072
	s_add_u32 s8, s14, 0xb0000
	s_addc_u32 s9, s15, 0
	s_mov_b32 m0, s22
	ds_read_b128 v[158:161], v141 offset:32768
	ds_read_b128 v[162:165], v141 offset:33792
	ds_read_b128 v[166:169], v141 offset:34816
	ds_read_b128 v[170:173], v141 offset:35840
	ds_read_b128 v[178:181], v141 offset:36864
	ds_read_b128 v[182:185], v141 offset:37888
	ds_read_b128 v[186:189], v141 offset:38912
	global_load_lds_dwordx4 v132, s[8:9]
	s_mov_b32 m0, s23
	ds_read_b128 v[190:193], v141 offset:39936
	global_load_lds_dwordx4 v130, s[8:9]
	s_waitcnt lgkmcnt(8)
	s_barrier
	s_waitcnt lgkmcnt(7)
	v_mfma_f32_16x16x32_bf16 v[124:127], v[142:145], v[158:161], v[124:127]
	v_mfma_f32_16x16x32_bf16 v[120:123], v[150:153], v[158:161], v[120:123]
	s_waitcnt lgkmcnt(5)
	v_mfma_f32_16x16x32_bf16 v[116:119], v[142:145], v[166:169], v[116:119]
	v_mfma_f32_16x16x32_bf16 v[112:115], v[150:153], v[166:169], v[112:115]
	s_waitcnt lgkmcnt(3)
	v_mfma_f32_16x16x32_bf16 v[100:103], v[142:145], v[178:181], v[100:103]
	v_mfma_f32_16x16x32_bf16 v[96:99], v[150:153], v[178:181], v[96:99]
	s_waitcnt lgkmcnt(1)
	v_mfma_f32_16x16x32_bf16 v[84:87], v[142:145], v[186:189], v[84:87]
	v_mfma_f32_16x16x32_bf16 v[80:83], v[150:153], v[186:189], v[80:83]
	v_mfma_f32_16x16x32_bf16 v[124:127], v[146:149], v[162:165], v[124:127]
	v_mfma_f32_16x16x32_bf16 v[120:123], v[154:157], v[162:165], v[120:123]
	v_mfma_f32_16x16x32_bf16 v[116:119], v[146:149], v[170:173], v[116:119]
	v_mfma_f32_16x16x32_bf16 v[112:115], v[154:157], v[170:173], v[112:115]
	v_mfma_f32_16x16x32_bf16 v[100:103], v[146:149], v[182:185], v[100:103]
	v_mfma_f32_16x16x32_bf16 v[96:99], v[154:157], v[182:185], v[96:99]
	s_waitcnt lgkmcnt(0)
	v_mfma_f32_16x16x32_bf16 v[84:87], v[146:149], v[190:193], v[84:87]
	v_mfma_f32_16x16x32_bf16 v[80:83], v[154:157], v[190:193], v[80:83]
	s_barrier
	v_add_u32_e32 v206, 0x1c000, v139
	s_add_i32 m0, s18, 0x18000
	ds_read_b128 v[194:197], v206
	ds_read_b128 v[198:201], v206 offset:1024
	ds_read_b128 v[202:205], v206 offset:2048
	global_load_lds_dwordx4 v176, s[98:99]
	s_add_i32 m0, s18, 0x1a000
	ds_read_b128 v[206:209], v206 offset:3072
	global_load_lds_dwordx4 v128, s[98:99]
	s_barrier
; #define PG8_STAGE(bufoff, gbase, voff) do { _Pragma("unroll") for (int _i = 0; _i < 2; ++_i) \
;         __builtin_amdgcn_global_load_lds((const unsigned*)((const char*)(gbase) + (voff)[_i]), (PG8_LAS unsigned*)(lds + (bufoff) + ldsw + _i * 8192), 16, 0, 0); } while (0)
; #define PG8_LDA(dst, b, h) do { _Pragma("unroll") for (int m = 0; m < 4; ++m) _Pragma("unroll") for (int k = 0; k < 2; ++k) dst[m][k] = *(const PG8_LAS bf16x8*)(lds + PG8_SA(b, h) + aoff + m * 2048 + k * 1024); } while (0)
; #define PG8_MMA(ai, bj, At, Bt) do { __builtin_amdgcn_s_setprio(1); _Pragma("unroll") for (int m = 0; m < 4; ++m) _Pragma("unroll") for (int n = 0; n < 2; ++n) _Pragma("unroll") for (int k = 0; k < 2; ++k) \
;         acc[ai][bj][m][n] = __builtin_amdgcn_mfma_f32_16x16x32_bf16(Bt[n][k], At[m][k], acc[ai][bj][m][n], 0, 0, 0); __builtin_amdgcn_s_setprio(0); } while (0)
; #define PG8_WAIT_V(n) asm volatile("s_waitcnt vmcnt(" #n ")" ::: "memory")
; #define PG8_WAIT_L(n) asm volatile("s_waitcnt lgkmcnt(" #n ")" ::: "memory")
; #define PG8_BAR __builtin_amdgcn_s_barrier()
; #define PG8_SCHED __builtin_amdgcn_sched_barrier(0)
; template <class Epi, class Sched>
; __device__ __forceinline__ void gemm_phase(PG8_LAS unsigned char* lds, const Gemm g, const Sched& S, const Epi& E) {
;     ...
;             PG8_BAR; PG8_WAIT_L(0); PG8_MMA(0, 1, At, B1); PG8_BAR;
;             PG8_LDA(At, 1, 1); PG8_STAGE(PG8_SA(1, 0), a3, voffA);
;             PG8_BAR; PG8_WAIT_L(0); PG8_MMA(1, 0, At, B0); PG8_BAR; PG8_SCHED;
;             PG8_STAGE(PG8_SB(1, 1), b3 + hstep, voffB);
;             PG8_WAIT_V(6); PG8_BAR; PG8_MMA(1, 1, At, B1); PG8_BAR;
;         }
	s_waitcnt lgkmcnt(3)
	v_mfma_f32_16x16x32_bf16 v[108:111], v[194:197], v[158:161], v[108:111]
	s_waitcnt lgkmcnt(1)
	v_mfma_f32_16x16x32_bf16 v[104:107], v[202:205], v[158:161], v[104:107]
	v_mfma_f32_16x16x32_bf16 v[92:95], v[194:197], v[166:169], v[92:95]
	v_mfma_f32_16x16x32_bf16 v[88:91], v[202:205], v[166:169], v[88:91]
	v_mfma_f32_16x16x32_bf16 v[76:79], v[194:197], v[178:181], v[76:79]
	v_mfma_f32_16x16x32_bf16 v[72:75], v[202:205], v[178:181], v[72:75]
	v_mfma_f32_16x16x32_bf16 v[68:71], v[194:197], v[186:189], v[68:71]
	v_mfma_f32_16x16x32_bf16 v[64:67], v[202:205], v[186:189], v[64:67]
	v_mfma_f32_16x16x32_bf16 v[108:111], v[198:201], v[162:165], v[108:111]
	s_waitcnt lgkmcnt(0)
	v_mfma_f32_16x16x32_bf16 v[104:107], v[206:209], v[162:165], v[104:107]
	v_mfma_f32_16x16x32_bf16 v[92:95], v[198:201], v[170:173], v[92:95]
	v_mfma_f32_16x16x32_bf16 v[88:91], v[206:209], v[170:173], v[88:91]
	v_mfma_f32_16x16x32_bf16 v[76:79], v[198:201], v[182:185], v[76:79]
	v_mfma_f32_16x16x32_bf16 v[72:75], v[206:209], v[182:185], v[72:75]
	v_mfma_f32_16x16x32_bf16 v[68:71], v[198:201], v[190:193], v[68:71]
	v_mfma_f32_16x16x32_bf16 v[64:67], v[206:209], v[190:193], v[64:67]
	s_mov_b32 m0, s27
	s_barrier
	ds_read_b128 v[158:161], v141 offset:49152
	ds_read_b128 v[162:165], v141 offset:50176
	ds_read_b128 v[166:169], v141 offset:51200
	ds_read_b128 v[170:173], v141 offset:52224
	ds_read_b128 v[178:181], v141 offset:53248
	ds_read_b128 v[182:185], v141 offset:54272
	ds_read_b128 v[186:189], v141 offset:55296
	global_load_lds_dwordx4 v132, s[100:101]
	s_mov_b32 m0, s28
	ds_read_b128 v[190:193], v141 offset:56320
	global_load_lds_dwordx4 v130, s[100:101]
	s_barrier
	s_waitcnt lgkmcnt(7)
	v_mfma_f32_16x16x32_bf16 v[60:63], v[142:145], v[158:161], v[60:63]
	v_mfma_f32_16x16x32_bf16 v[56:59], v[150:153], v[158:161], v[56:59]
	s_waitcnt lgkmcnt(5)
	v_mfma_f32_16x16x32_bf16 v[52:55], v[142:145], v[166:169], v[52:55]
	v_mfma_f32_16x16x32_bf16 v[48:51], v[150:153], v[166:169], v[48:51]
	s_waitcnt lgkmcnt(3)
	v_mfma_f32_16x16x32_bf16 v[36:39], v[142:145], v[178:181], v[36:39]
	v_mfma_f32_16x16x32_bf16 v[32:35], v[150:153], v[178:181], v[32:35]
	s_waitcnt lgkmcnt(1)
	v_mfma_f32_16x16x32_bf16 v[20:23], v[142:145], v[186:189], v[20:23]
	v_mfma_f32_16x16x32_bf16 v[16:19], v[150:153], v[186:189], v[16:19]
	v_mfma_f32_16x16x32_bf16 v[60:63], v[146:149], v[162:165], v[60:63]
	v_mfma_f32_16x16x32_bf16 v[56:59], v[154:157], v[162:165], v[56:59]
	v_mfma_f32_16x16x32_bf16 v[52:55], v[146:149], v[170:173], v[52:55]
	v_mfma_f32_16x16x32_bf16 v[48:51], v[154:157], v[170:173], v[48:51]
	v_mfma_f32_16x16x32_bf16 v[36:39], v[146:149], v[182:185], v[36:39]
	v_mfma_f32_16x16x32_bf16 v[32:35], v[154:157], v[182:185], v[32:35]
	s_waitcnt lgkmcnt(0)
	v_mfma_f32_16x16x32_bf16 v[20:23], v[146:149], v[190:193], v[20:23]
	v_mfma_f32_16x16x32_bf16 v[16:19], v[154:157], v[190:193], v[16:19]
	s_barrier
	s_add_u32 s8, s12, 0xb0080
	s_addc_u32 s9, s13, 0
	s_add_i32 m0, s18, 0x1c000
	s_nop 0
	global_load_lds_dwordx4 v176, s[8:9]
	s_add_i32 m0, s18, 0x1e000
	s_nop 0
	global_load_lds_dwordx4 v128, s[8:9]
	s_waitcnt vmcnt(6)
	s_barrier
	v_mfma_f32_16x16x32_bf16 v[44:47], v[194:197], v[158:161], v[44:47]
	v_mfma_f32_16x16x32_bf16 v[40:43], v[202:205], v[158:161], v[40:43]
	v_mfma_f32_16x16x32_bf16 v[28:31], v[194:197], v[166:169], v[28:31]
	v_mfma_f32_16x16x32_bf16 v[24:27], v[202:205], v[166:169], v[24:27]
	v_mfma_f32_16x16x32_bf16 v[12:15], v[194:197], v[178:181], v[12:15]
	v_mfma_f32_16x16x32_bf16 v[8:11], v[202:205], v[178:181], v[8:11]
	v_mfma_f32_16x16x32_bf16 v[4:7], v[194:197], v[186:189], v[4:7]
	v_mfma_f32_16x16x32_bf16 v[0:3], v[202:205], v[186:189], v[0:3]
	v_mfma_f32_16x16x32_bf16 v[44:47], v[198:201], v[162:165], v[44:47]
	v_mfma_f32_16x16x32_bf16 v[40:43], v[206:209], v[162:165], v[40:43]
	v_mfma_f32_16x16x32_bf16 v[28:31], v[198:201], v[170:173], v[28:31]
	v_mfma_f32_16x16x32_bf16 v[24:27], v[206:209], v[170:173], v[24:27]
	v_mfma_f32_16x16x32_bf16 v[12:15], v[198:201], v[182:185], v[12:15]
	v_mfma_f32_16x16x32_bf16 v[8:11], v[206:209], v[182:185], v[8:11]
	v_mfma_f32_16x16x32_bf16 v[4:7], v[198:201], v[190:193], v[4:7]
	v_mfma_f32_16x16x32_bf16 v[0:3], v[206:209], v[190:193], v[0:3]
	s_add_i32 s45, s45, 2
	s_add_u32 s43, s43, 0x100
	s_addc_u32 s44, s44, 0
	s_cmp_gt_u32 s45, 41
	s_mov_b64 s[8:9], s[10:11]
	s_barrier

; #define PG8_STAGE(bufoff, gbase, voff) do { _Pragma("unroll") for (int _i = 0; _i < 2; ++_i) \
;         __builtin_amdgcn_global_load_lds((const unsigned*)((const char*)(gbase) + (voff)[_i]), (PG8_LAS unsigned*)(lds + (bufoff) + ldsw + _i * 8192), 16, 0, 0); } while (0)
; #define PG8_LDA(dst, b, h) do { _Pragma("unroll") for (int m = 0; m < 4; ++m) _Pragma("unroll") for (int k = 0; k < 2; ++k) dst[m][k] = *(const PG8_LAS bf16x8*)(lds + PG8_SA(b, h) + aoff + m * 2048 + k * 1024); } while (0)
; #define PG8_LDB(dst, b, h) do { _Pragma("unroll") for (int n = 0; n < 2; ++n) _Pragma("unroll") for (int k = 0; k < 2; ++k) dst[n][k] = *(const PG8_LAS bf16x8*)(lds + PG8_SB(b, h) + boff + n * 2048 + k * 1024); } while (0)
; #define PG8_MMA(ai, bj, At, Bt) do { __builtin_amdgcn_s_setprio(1); _Pragma("unroll") for (int m = 0; m < 4; ++m) _Pragma("unroll") for (int n = 0; n < 2; ++n) _Pragma("unroll") for (int k = 0; k < 2; ++k) \
;         acc[ai][bj][m][n] = __builtin_amdgcn_mfma_f32_16x16x32_bf16(Bt[n][k], At[m][k], acc[ai][bj][m][n], 0, 0, 0); __builtin_amdgcn_s_setprio(0); } while (0)
; template <class Epi, class Sched>
; __device__ __forceinline__ void gemm_phase(PG8_LAS unsigned char* lds, const Gemm g, const Sched& S, const Epi& E) {
;     ...
;         const bool has_next = S.next(ui + 1, nxt);
;         const char* nA = has_next ? (const char*)g.A + (size_t)nxt.pm * tstep : cA; const char* nB = has_next ? (const char*)g.Bt + (size_t)nxt.pn * tstep : cB;
;         for (int t = 0; t < nt; t += 2) {
;             const bool last = (t == nt - 2);
;             const char* a1 = cA + (size_t)(t + 1) * kstep;
;             const char* a2 = last ? nA : cA + (size_t)(t + 2) * kstep; const char* b2 = last ? nB : cB + (size_t)(t + 2) * kstep;
;             const char* a3 = a2 + kstep; const char* b3 = b2 + kstep;
;             if (last && has_next) S.a_ready(nxt);
;             PG8_LDB(B0, 0, 0); PG8_SCHED; PG8_LDA(At, 0, 0); PG8_STAGE(PG8_SA(1, 1), a1 + hstep, voffA);
;             PG8_WAIT_L(8); PG8_BAR; PG8_WAIT_L(0); PG8_MMA(0, 0, At, B0); PG8_BAR; PG8_SCHED;
;             PG8_LDB(B1, 0, 1); PG8_STAGE(PG8_SB(0, 0), b2, voffB);
;             PG8_BAR; PG8_WAIT_L(0); PG8_MMA(0, 1, At, B1); PG8_BAR;
;             PG8_LDA(At, 0, 1); PG8_STAGE(PG8_SA(0, 0), a2, voffA);
;             PG8_BAR; PG8_WAIT_L(0); PG8_MMA(1, 0, At, B0); PG8_BAR; PG8_SCHED;
.LBB0_113:
	v_mov_b64_e32 v[0:1], 0x580
	s_ashr_i32 s5, s4, 31
	v_cmp_lt_i64_e32 vcc, s[6:7], v[0:1]
	s_lshl_b64 s[6:7], s[4:5], 19
	s_add_u32 s6, s94, s6
	s_addc_u32 s7, s95, s7
	s_and_b64 s[8:9], vcc, exec
	s_cselect_b32 s5, s7, s13
	s_cselect_b32 s40, s6, s12
	s_ashr_i32 s1, s0, 31
	s_lshl_b64 s[8:9], s[0:1], 19
	v_readlane_b32 s16, v253, 12
	v_readlane_b32 s17, v253, 13
	s_add_u32 s8, s16, s8
	s_addc_u32 s9, s17, s9
	s_and_b64 s[16:17], vcc, exec
	s_cselect_b32 s1, s9, s15
	s_cselect_b32 s41, s8, s14
	s_add_u32 s12, s12, 0x40080
	s_addc_u32 s13, s13, 0
	s_add_u32 s43, s14, 0x100
	s_addc_u32 s44, s15, 0
	s_mov_b32 s45, -2
	s_add_u32 s14, s12, 0xfffc0080
	s_addc_u32 s15, s13, -1
	v_add_u32_e32 v154, 0x10000, v143
	ds_read_b128 v[138:141], v154
	ds_read_b128 v[146:149], v154 offset:1024
	ds_read_b128 v[150:153], v154 offset:2048
	ds_read_b128 v[154:157], v154 offset:3072
	s_cmp_eq_u32 s45, 12
	s_cselect_b32 s17, s5, s15
	s_cselect_b32 s16, s40, s14
	s_cselect_b32 s15, s1, s44
	s_cselect_b32 s14, s41, s43
	s_add_i32 m0, s11, 0xc000
	ds_read_b128 v[158:161], v145
	ds_read_b128 v[162:165], v145 offset:1024
	ds_read_b128 v[166:169], v145 offset:2048
	ds_read_b128 v[170:173], v145 offset:3072
	ds_read_b128 v[178:181], v145 offset:4096
	ds_read_b128 v[182:185], v145 offset:5120
	ds_read_b128 v[186:189], v145 offset:6144
	global_load_lds_dwordx4 v134, s[12:13]
	s_add_i32 m0, s11, 0xe000
	ds_read_b128 v[190:193], v145 offset:7168
	global_load_lds_dwordx4 v136, s[12:13]
	s_waitcnt lgkmcnt(8)
	s_barrier
	s_waitcnt lgkmcnt(7)
	v_mfma_f32_16x16x32_bf16 v[124:127], v[138:141], v[158:161], 0
	v_mfma_f32_16x16x32_bf16 v[116:119], v[150:153], v[158:161], 0
	s_waitcnt lgkmcnt(5)
	v_mfma_f32_16x16x32_bf16 v[108:111], v[138:141], v[166:169], 0
	v_mfma_f32_16x16x32_bf16 v[100:103], v[150:153], v[166:169], 0
	s_waitcnt lgkmcnt(3)
	v_mfma_f32_16x16x32_bf16 v[92:95], v[138:141], v[178:181], 0
	v_mfma_f32_16x16x32_bf16 v[84:87], v[150:153], v[178:181], 0
	s_waitcnt lgkmcnt(1)
	v_mfma_f32_16x16x32_bf16 v[76:79], v[138:141], v[186:189], 0
	v_mfma_f32_16x16x32_bf16 v[68:71], v[150:153], v[186:189], 0
	v_mfma_f32_16x16x32_bf16 v[124:127], v[146:149], v[162:165], v[124:127]
	v_mfma_f32_16x16x32_bf16 v[116:119], v[154:157], v[162:165], v[116:119]
	v_mfma_f32_16x16x32_bf16 v[108:111], v[146:149], v[170:173], v[108:111]
	v_mfma_f32_16x16x32_bf16 v[100:103], v[154:157], v[170:173], v[100:103]
	v_mfma_f32_16x16x32_bf16 v[92:95], v[146:149], v[182:185], v[92:95]
	v_mfma_f32_16x16x32_bf16 v[84:87], v[154:157], v[182:185], v[84:87]
	s_waitcnt lgkmcnt(0)
	v_mfma_f32_16x16x32_bf16 v[76:79], v[146:149], v[190:193], v[76:79]
	v_mfma_f32_16x16x32_bf16 v[68:71], v[154:157], v[190:193], v[68:71]
	s_barrier
	s_add_i32 s48, 0, 0x14000
	v_add_u32_e32 v174, 0x14000, v143
	ds_read_b128 v[194:197], v174
	ds_read_b128 v[198:201], v174 offset:1024
	s_add_u32 s98, s14, 0x80
	s_addc_u32 s99, s15, 0
	s_add_i32 m0, s20, 0x10000
	ds_read_b128 v[202:205], v174 offset:2048
	global_load_lds_dwordx4 v176, s[14:15]
	s_add_i32 m0, s20, 0x12000
	ds_read_b128 v[206:209], v174 offset:3072
	global_load_lds_dwordx4 v128, s[14:15]
	s_barrier
	s_waitcnt lgkmcnt(3)
	v_mfma_f32_16x16x32_bf16 v[120:123], v[194:197], v[158:161], 0
	s_waitcnt lgkmcnt(1)
	v_mfma_f32_16x16x32_bf16 v[112:115], v[202:205], v[158:161], 0
	v_mfma_f32_16x16x32_bf16 v[104:107], v[194:197], v[166:169], 0
	v_mfma_f32_16x16x32_bf16 v[96:99], v[202:205], v[166:169], 0
	v_mfma_f32_16x16x32_bf16 v[88:91], v[194:197], v[178:181], 0
	v_mfma_f32_16x16x32_bf16 v[80:83], v[202:205], v[178:181], 0
	v_mfma_f32_16x16x32_bf16 v[72:75], v[194:197], v[186:189], 0
	v_mfma_f32_16x16x32_bf16 v[64:67], v[202:205], v[186:189], 0
	v_mfma_f32_16x16x32_bf16 v[120:123], v[198:201], v[162:165], v[120:123]
	s_waitcnt lgkmcnt(0)
	v_mfma_f32_16x16x32_bf16 v[112:115], v[206:209], v[162:165], v[112:115]
	v_mfma_f32_16x16x32_bf16 v[104:107], v[198:201], v[170:173], v[104:107]
	v_mfma_f32_16x16x32_bf16 v[96:99], v[206:209], v[170:173], v[96:99]
	v_mfma_f32_16x16x32_bf16 v[88:91], v[198:201], v[182:185], v[88:91]
	v_mfma_f32_16x16x32_bf16 v[80:83], v[206:209], v[182:185], v[80:83]
	v_mfma_f32_16x16x32_bf16 v[72:75], v[198:201], v[190:193], v[72:75]
	v_mfma_f32_16x16x32_bf16 v[64:67], v[206:209], v[190:193], v[64:67]
	s_mov_b32 m0, s11
	s_add_u32 s100, s16, 0x80
	s_addc_u32 s101, s17, 0
	s_barrier
	ds_read_b128 v[158:161], v145 offset:16384
	ds_read_b128 v[162:165], v145 offset:17408
	ds_read_b128 v[166:169], v145 offset:18432
	ds_read_b128 v[170:173], v145 offset:19456
	ds_read_b128 v[178:181], v145 offset:20480
	ds_read_b128 v[182:185], v145 offset:21504
	ds_read_b128 v[186:189], v145 offset:22528
	global_load_lds_dwordx4 v132, s[16:17]
	s_mov_b32 m0, s22
	ds_read_b128 v[190:193], v145 offset:23552
	global_load_lds_dwordx4 v130, s[16:17]
	s_barrier
	s_waitcnt lgkmcnt(7)
	v_mfma_f32_16x16x32_bf16 v[60:63], v[138:141], v[158:161], 0
	v_mfma_f32_16x16x32_bf16 v[52:55], v[150:153], v[158:161], 0
	s_waitcnt lgkmcnt(5)
	v_mfma_f32_16x16x32_bf16 v[44:47], v[138:141], v[166:169], 0
	v_mfma_f32_16x16x32_bf16 v[36:39], v[150:153], v[166:169], 0
	s_waitcnt lgkmcnt(3)
	v_mfma_f32_16x16x32_bf16 v[28:31], v[138:141], v[178:181], 0
	v_mfma_f32_16x16x32_bf16 v[20:23], v[150:153], v[178:181], 0
	s_waitcnt lgkmcnt(1)
	v_mfma_f32_16x16x32_bf16 v[12:15], v[138:141], v[186:189], 0
	v_mfma_f32_16x16x32_bf16 v[4:7], v[150:153], v[186:189], 0
	v_mfma_f32_16x16x32_bf16 v[60:63], v[146:149], v[162:165], v[60:63]
	v_mfma_f32_16x16x32_bf16 v[52:55], v[154:157], v[162:165], v[52:55]
	v_mfma_f32_16x16x32_bf16 v[44:47], v[146:149], v[170:173], v[44:47]
	v_mfma_f32_16x16x32_bf16 v[36:39], v[154:157], v[170:173], v[36:39]
	v_mfma_f32_16x16x32_bf16 v[28:31], v[146:149], v[182:185], v[28:31]
	v_mfma_f32_16x16x32_bf16 v[20:23], v[154:157], v[182:185], v[20:23]
	s_waitcnt lgkmcnt(0)
	v_mfma_f32_16x16x32_bf16 v[12:15], v[146:149], v[190:193], v[12:15]
	v_mfma_f32_16x16x32_bf16 v[4:7], v[154:157], v[190:193], v[4:7]
	s_barrier
; #define PG8_STAGE(bufoff, gbase, voff) do { _Pragma("unroll") for (int _i = 0; _i < 2; ++_i) \
;         __builtin_amdgcn_global_load_lds((const unsigned*)((const char*)(gbase) + (voff)[_i]), (PG8_LAS unsigned*)(lds + (bufoff) + ldsw + _i * 8192), 16, 0, 0); } while (0)
; #define PG8_LDA(dst, b, h) do { _Pragma("unroll") for (int m = 0; m < 4; ++m) _Pragma("unroll") for (int k = 0; k < 2; ++k) dst[m][k] = *(const PG8_LAS bf16x8*)(lds + PG8_SA(b, h) + aoff + m * 2048 + k * 1024); } while (0)
; #define PG8_LDB(dst, b, h) do { _Pragma("unroll") for (int n = 0; n < 2; ++n) _Pragma("unroll") for (int k = 0; k < 2; ++k) dst[n][k] = *(const PG8_LAS bf16x8*)(lds + PG8_SB(b, h) + boff + n * 2048 + k * 1024); } while (0)
; #define PG8_MMA(ai, bj, At, Bt) do { __builtin_amdgcn_s_setprio(1); _Pragma("unroll") for (int m = 0; m < 4; ++m) _Pragma("unroll") for (int n = 0; n < 2; ++n) _Pragma("unroll") for (int k = 0; k < 2; ++k) \
;         acc[ai][bj][m][n] = __builtin_amdgcn_mfma_f32_16x16x32_bf16(Bt[n][k], At[m][k], acc[ai][bj][m][n], 0, 0, 0); __builtin_amdgcn_s_setprio(0); } while (0)
; #define PG8_WAIT_V(n) asm volatile("s_waitcnt vmcnt(" #n ")" ::: "memory")
; #define PG8_WAIT_L(n) asm volatile("s_waitcnt lgkmcnt(" #n ")" ::: "memory")
; #define PG8_BAR __builtin_amdgcn_s_barrier()
; #define PG8_SCHED __builtin_amdgcn_sched_barrier(0)
; template <class Epi, class Sched>
; __device__ __forceinline__ void gemm_phase(PG8_LAS unsigned char* lds, const Gemm g, const Sched& S, const Epi& E) {
;     ...
;             PG8_BAR; PG8_WAIT_L(0); PG8_MMA(1, 0, At, B0); PG8_BAR; PG8_SCHED;
;             PG8_STAGE(PG8_SB(0, 1), b2 + hstep, voffB);
;             PG8_WAIT_V(6); PG8_BAR; PG8_MMA(1, 1, At, B1); PG8_BAR;
;             PG8_LDB(B0, 1, 0); PG8_SCHED; PG8_LDA(At, 1, 0); PG8_STAGE(PG8_SA(0, 1), a2 + hstep, voffA);
;             PG8_WAIT_L(8); PG8_BAR; PG8_WAIT_L(0); PG8_MMA(0, 0, At, B0); PG8_BAR; PG8_SCHED;
;             PG8_LDB(B1, 1, 1); PG8_STAGE(PG8_SB(1, 0), b3, voffB);
;             PG8_BAR; PG8_WAIT_L(0); PG8_MMA(0, 1, At, B1); PG8_BAR;
	s_add_u32 s46, s14, 0x40000
	s_addc_u32 s47, s15, 0
	s_add_i32 m0, s20, 0x14000
	s_nop 0
	global_load_lds_dwordx4 v176, s[46:47]
	s_add_i32 m0, s20, 0x16000
	s_nop 0
	global_load_lds_dwordx4 v128, s[46:47]
	s_waitcnt vmcnt(6)
	s_barrier
	v_mfma_f32_16x16x32_bf16 v[56:59], v[194:197], v[158:161], 0
	v_mfma_f32_16x16x32_bf16 v[48:51], v[202:205], v[158:161], 0
	v_mfma_f32_16x16x32_bf16 v[40:43], v[194:197], v[166:169], 0
	v_mfma_f32_16x16x32_bf16 v[32:35], v[202:205], v[166:169], 0
	v_mfma_f32_16x16x32_bf16 v[24:27], v[194:197], v[178:181], 0
	v_mfma_f32_16x16x32_bf16 v[16:19], v[202:205], v[178:181], 0
	v_mfma_f32_16x16x32_bf16 v[8:11], v[194:197], v[186:189], 0
	v_mfma_f32_16x16x32_bf16 v[0:3], v[202:205], v[186:189], 0
	v_mfma_f32_16x16x32_bf16 v[56:59], v[198:201], v[162:165], v[56:59]
	v_mfma_f32_16x16x32_bf16 v[48:51], v[206:209], v[162:165], v[48:51]
	v_mfma_f32_16x16x32_bf16 v[40:43], v[198:201], v[170:173], v[40:43]
	v_mfma_f32_16x16x32_bf16 v[32:35], v[206:209], v[170:173], v[32:35]
	v_mfma_f32_16x16x32_bf16 v[24:27], v[198:201], v[182:185], v[24:27]
	v_mfma_f32_16x16x32_bf16 v[16:19], v[206:209], v[182:185], v[16:19]
	v_mfma_f32_16x16x32_bf16 v[8:11], v[198:201], v[190:193], v[8:11]
	v_mfma_f32_16x16x32_bf16 v[0:3], v[206:209], v[190:193], v[0:3]
	v_add_u32_e32 v154, 0x18000, v143
	s_barrier
	ds_read_b128 v[138:141], v154
	ds_read_b128 v[146:149], v154 offset:1024
	ds_read_b128 v[150:153], v154 offset:2048
	ds_read_b128 v[154:157], v154 offset:3072
	s_add_u32 s16, s16, 0x40000
	s_addc_u32 s17, s17, 0
	s_mov_b32 m0, s23
	ds_read_b128 v[158:161], v145 offset:32768
	ds_read_b128 v[162:165], v145 offset:33792
	ds_read_b128 v[166:169], v145 offset:34816
	ds_read_b128 v[170:173], v145 offset:35840
	ds_read_b128 v[178:181], v145 offset:36864
	ds_read_b128 v[182:185], v145 offset:37888
	ds_read_b128 v[186:189], v145 offset:38912
	global_load_lds_dwordx4 v132, s[16:17]
	s_mov_b32 m0, s26
	ds_read_b128 v[190:193], v145 offset:39936
	global_load_lds_dwordx4 v130, s[16:17]
	s_waitcnt lgkmcnt(8)
	s_barrier
	s_waitcnt lgkmcnt(7)
	v_mfma_f32_16x16x32_bf16 v[124:127], v[138:141], v[158:161], v[124:127]
	v_mfma_f32_16x16x32_bf16 v[116:119], v[150:153], v[158:161], v[116:119]
	s_waitcnt lgkmcnt(5)
	v_mfma_f32_16x16x32_bf16 v[108:111], v[138:141], v[166:169], v[108:111]
	v_mfma_f32_16x16x32_bf16 v[100:103], v[150:153], v[166:169], v[100:103]
	s_waitcnt lgkmcnt(3)
	v_mfma_f32_16x16x32_bf16 v[92:95], v[138:141], v[178:181], v[92:95]
	v_mfma_f32_16x16x32_bf16 v[84:87], v[150:153], v[178:181], v[84:87]
	s_waitcnt lgkmcnt(1)
	v_mfma_f32_16x16x32_bf16 v[76:79], v[138:141], v[186:189], v[76:79]
	v_mfma_f32_16x16x32_bf16 v[68:71], v[150:153], v[186:189], v[68:71]
	v_mfma_f32_16x16x32_bf16 v[124:127], v[146:149], v[162:165], v[124:127]
	v_mfma_f32_16x16x32_bf16 v[116:119], v[154:157], v[162:165], v[116:119]
	v_mfma_f32_16x16x32_bf16 v[108:111], v[146:149], v[170:173], v[108:111]
	v_mfma_f32_16x16x32_bf16 v[100:103], v[154:157], v[170:173], v[100:103]
	v_mfma_f32_16x16x32_bf16 v[92:95], v[146:149], v[182:185], v[92:95]
	v_mfma_f32_16x16x32_bf16 v[84:87], v[154:157], v[182:185], v[84:87]
	s_waitcnt lgkmcnt(0)
	v_mfma_f32_16x16x32_bf16 v[76:79], v[146:149], v[190:193], v[76:79]
	v_mfma_f32_16x16x32_bf16 v[68:71], v[154:157], v[190:193], v[68:71]
	s_barrier
	v_add_u32_e32 v206, 0x1c000, v143
	s_add_i32 m0, s20, 0x18000
	ds_read_b128 v[194:197], v206
	ds_read_b128 v[198:201], v206 offset:1024
	ds_read_b128 v[202:205], v206 offset:2048
	global_load_lds_dwordx4 v176, s[98:99]
	s_add_i32 m0, s20, 0x1a000
	ds_read_b128 v[206:209], v206 offset:3072
	global_load_lds_dwordx4 v128, s[98:99]
	s_barrier
; #define PG8_STAGE(bufoff, gbase, voff) do { _Pragma("unroll") for (int _i = 0; _i < 2; ++_i) \
;         __builtin_amdgcn_global_load_lds((const unsigned*)((const char*)(gbase) + (voff)[_i]), (PG8_LAS unsigned*)(lds + (bufoff) + ldsw + _i * 8192), 16, 0, 0); } while (0)
; #define PG8_LDA(dst, b, h) do { _Pragma("unroll") for (int m = 0; m < 4; ++m) _Pragma("unroll") for (int k = 0; k < 2; ++k) dst[m][k] = *(const PG8_LAS bf16x8*)(lds + PG8_SA(b, h) + aoff + m * 2048 + k * 1024); } while (0)
; #define PG8_MMA(ai, bj, At, Bt) do { __builtin_amdgcn_s_setprio(1); _Pragma("unroll") for (int m = 0; m < 4; ++m) _Pragma("unroll") for (int n = 0; n < 2; ++n) _Pragma("unroll") for (int k = 0; k < 2; ++k) \
;         acc[ai][bj][m][n] = __builtin_amdgcn_mfma_f32_16x16x32_bf16(Bt[n][k], At[m][k], acc[ai][bj][m][n], 0, 0, 0); __builtin_amdgcn_s_setprio(0); } while (0)
; #define PG8_WAIT_V(n) asm volatile("s_waitcnt vmcnt(" #n ")" ::: "memory")
; #define PG8_WAIT_L(n) asm volatile("s_waitcnt lgkmcnt(" #n ")" ::: "memory")
; #define PG8_BAR __builtin_amdgcn_s_barrier()
; #define PG8_SCHED __builtin_amdgcn_sched_barrier(0)
; template <class Epi, class Sched>
; __device__ __forceinline__ void gemm_phase(PG8_LAS unsigned char* lds, const Gemm g, const Sched& S, const Epi& E) {
;     ...
;             PG8_BAR; PG8_WAIT_L(0); PG8_MMA(0, 1, At, B1); PG8_BAR;
;             PG8_LDA(At, 1, 1); PG8_STAGE(PG8_SA(1, 0), a3, voffA);
;             PG8_BAR; PG8_WAIT_L(0); PG8_MMA(1, 0, At, B0); PG8_BAR; PG8_SCHED;
;             PG8_STAGE(PG8_SB(1, 1), b3 + hstep, voffB);
;             PG8_WAIT_V(6); PG8_BAR; PG8_MMA(1, 1, At, B1); PG8_BAR;
;         }
	s_waitcnt lgkmcnt(3)
	v_mfma_f32_16x16x32_bf16 v[120:123], v[194:197], v[158:161], v[120:123]
	s_waitcnt lgkmcnt(1)
	v_mfma_f32_16x16x32_bf16 v[112:115], v[202:205], v[158:161], v[112:115]
	v_mfma_f32_16x16x32_bf16 v[104:107], v[194:197], v[166:169], v[104:107]
	v_mfma_f32_16x16x32_bf16 v[96:99], v[202:205], v[166:169], v[96:99]
	v_mfma_f32_16x16x32_bf16 v[88:91], v[194:197], v[178:181], v[88:91]
	v_mfma_f32_16x16x32_bf16 v[80:83], v[202:205], v[178:181], v[80:83]
	v_mfma_f32_16x16x32_bf16 v[72:75], v[194:197], v[186:189], v[72:75]
	v_mfma_f32_16x16x32_bf16 v[64:67], v[202:205], v[186:189], v[64:67]
	v_mfma_f32_16x16x32_bf16 v[120:123], v[198:201], v[162:165], v[120:123]
	s_waitcnt lgkmcnt(0)
	v_mfma_f32_16x16x32_bf16 v[112:115], v[206:209], v[162:165], v[112:115]
	v_mfma_f32_16x16x32_bf16 v[104:107], v[198:201], v[170:173], v[104:107]
	v_mfma_f32_16x16x32_bf16 v[96:99], v[206:209], v[170:173], v[96:99]
	v_mfma_f32_16x16x32_bf16 v[88:91], v[198:201], v[182:185], v[88:91]
	v_mfma_f32_16x16x32_bf16 v[80:83], v[206:209], v[182:185], v[80:83]
	v_mfma_f32_16x16x32_bf16 v[72:75], v[198:201], v[190:193], v[72:75]
	v_mfma_f32_16x16x32_bf16 v[64:67], v[206:209], v[190:193], v[64:67]
	s_mov_b32 m0, s28
	s_barrier
	ds_read_b128 v[158:161], v145 offset:49152
	ds_read_b128 v[162:165], v145 offset:50176
	ds_read_b128 v[166:169], v145 offset:51200
	ds_read_b128 v[170:173], v145 offset:52224
	ds_read_b128 v[178:181], v145 offset:53248
	ds_read_b128 v[182:185], v145 offset:54272
	ds_read_b128 v[186:189], v145 offset:55296
	global_load_lds_dwordx4 v132, s[100:101]
	s_mov_b32 m0, s29
	ds_read_b128 v[190:193], v145 offset:56320
	global_load_lds_dwordx4 v130, s[100:101]
	s_barrier
	s_waitcnt lgkmcnt(7)
	v_mfma_f32_16x16x32_bf16 v[60:63], v[138:141], v[158:161], v[60:63]
	v_mfma_f32_16x16x32_bf16 v[52:55], v[150:153], v[158:161], v[52:55]
	s_waitcnt lgkmcnt(5)
	v_mfma_f32_16x16x32_bf16 v[44:47], v[138:141], v[166:169], v[44:47]
	v_mfma_f32_16x16x32_bf16 v[36:39], v[150:153], v[166:169], v[36:39]
	s_waitcnt lgkmcnt(3)
	v_mfma_f32_16x16x32_bf16 v[28:31], v[138:141], v[178:181], v[28:31]
	v_mfma_f32_16x16x32_bf16 v[20:23], v[150:153], v[178:181], v[20:23]
	s_waitcnt lgkmcnt(1)
	v_mfma_f32_16x16x32_bf16 v[12:15], v[138:141], v[186:189], v[12:15]
	v_mfma_f32_16x16x32_bf16 v[4:7], v[150:153], v[186:189], v[4:7]
	v_mfma_f32_16x16x32_bf16 v[60:63], v[146:149], v[162:165], v[60:63]
	v_mfma_f32_16x16x32_bf16 v[52:55], v[154:157], v[162:165], v[52:55]
	v_mfma_f32_16x16x32_bf16 v[44:47], v[146:149], v[170:173], v[44:47]
	v_mfma_f32_16x16x32_bf16 v[36:39], v[154:157], v[170:173], v[36:39]
	v_mfma_f32_16x16x32_bf16 v[28:31], v[146:149], v[182:185], v[28:31]
	v_mfma_f32_16x16x32_bf16 v[20:23], v[154:157], v[182:185], v[20:23]
	s_waitcnt lgkmcnt(0)
	v_mfma_f32_16x16x32_bf16 v[12:15], v[146:149], v[190:193], v[12:15]
	v_mfma_f32_16x16x32_bf16 v[4:7], v[154:157], v[190:193], v[4:7]
	s_barrier
	s_add_u32 s14, s14, 0x40080
	s_addc_u32 s15, s15, 0
	s_add_i32 m0, s20, 0x1c000
	s_nop 0
	global_load_lds_dwordx4 v176, s[14:15]
	s_add_i32 m0, s20, 0x1e000
	s_nop 0
	global_load_lds_dwordx4 v128, s[14:15]
	s_waitcnt vmcnt(6)
	s_barrier
	v_mfma_f32_16x16x32_bf16 v[56:59], v[194:197], v[158:161], v[56:59]
	v_mfma_f32_16x16x32_bf16 v[48:51], v[202:205], v[158:161], v[48:51]
	v_mfma_f32_16x16x32_bf16 v[40:43], v[194:197], v[166:169], v[40:43]
	v_mfma_f32_16x16x32_bf16 v[32:35], v[202:205], v[166:169], v[32:35]
	v_mfma_f32_16x16x32_bf16 v[24:27], v[194:197], v[178:181], v[24:27]
	v_mfma_f32_16x16x32_bf16 v[16:19], v[202:205], v[178:181], v[16:19]
	v_mfma_f32_16x16x32_bf16 v[8:11], v[194:197], v[186:189], v[8:11]
	v_mfma_f32_16x16x32_bf16 v[0:3], v[202:205], v[186:189], v[0:3]
	v_mfma_f32_16x16x32_bf16 v[56:59], v[198:201], v[162:165], v[56:59]
	v_mfma_f32_16x16x32_bf16 v[48:51], v[206:209], v[162:165], v[48:51]
	v_mfma_f32_16x16x32_bf16 v[40:43], v[198:201], v[170:173], v[40:43]
	v_mfma_f32_16x16x32_bf16 v[32:35], v[206:209], v[170:173], v[32:35]
	v_mfma_f32_16x16x32_bf16 v[24:27], v[198:201], v[182:185], v[24:27]
	v_mfma_f32_16x16x32_bf16 v[16:19], v[206:209], v[182:185], v[16:19]
	v_mfma_f32_16x16x32_bf16 v[8:11], v[198:201], v[190:193], v[8:11]
	v_mfma_f32_16x16x32_bf16 v[0:3], v[206:209], v[190:193], v[0:3]
	s_add_i32 s45, s45, 2
	s_add_u32 s12, s12, 0x100
	s_addc_u32 s13, s13, 0
	s_add_u32 s43, s43, 0x100
	s_addc_u32 s44, s44, 0
	s_cmp_gt_u32 s45, 13
	s_barrier

; #define PG8_STAGE(bufoff, gbase, voff) do { _Pragma("unroll") for (int _i = 0; _i < 2; ++_i) \
;         __builtin_amdgcn_global_load_lds((const unsigned*)((const char*)(gbase) + (voff)[_i]), (PG8_LAS unsigned*)(lds + (bufoff) + ldsw + _i * 8192), 16, 0, 0); } while (0)
; #define PG8_LDA(dst, b, h) do { _Pragma("unroll") for (int m = 0; m < 4; ++m) _Pragma("unroll") for (int k = 0; k < 2; ++k) dst[m][k] = *(const PG8_LAS bf16x8*)(lds + PG8_SA(b, h) + aoff + m * 2048 + k * 1024); } while (0)
; #define PG8_LDB(dst, b, h) do { _Pragma("unroll") for (int n = 0; n < 2; ++n) _Pragma("unroll") for (int k = 0; k < 2; ++k) dst[n][k] = *(const PG8_LAS bf16x8*)(lds + PG8_SB(b, h) + boff + n * 2048 + k * 1024); } while (0)
; #define PG8_MMA(ai, bj, At, Bt) do { __builtin_amdgcn_s_setprio(1); _Pragma("unroll") for (int m = 0; m < 4; ++m) _Pragma("unroll") for (int n = 0; n < 2; ++n) _Pragma("unroll") for (int k = 0; k < 2; ++k) \
;         acc[ai][bj][m][n] = __builtin_amdgcn_mfma_f32_16x16x32_bf16(Bt[n][k], At[m][k], acc[ai][bj][m][n], 0, 0, 0); __builtin_amdgcn_s_setprio(0); } while (0)
; template <class Epi, class Sched>
; __device__ __forceinline__ void gemm_phase(PG8_LAS unsigned char* lds, const Gemm g, const Sched& S, const Epi& E) {
;     ...
;         const bool has_next = S.next(ui + 1, nxt);
;         const char* nA = has_next ? (const char*)g.A + (size_t)nxt.pm * tstep : cA; const char* nB = has_next ? (const char*)g.Bt + (size_t)nxt.pn * tstep : cB;
;         for (int t = 0; t < nt; t += 2) {
;             const bool last = (t == nt - 2);
;             const char* a1 = cA + (size_t)(t + 1) * kstep;
;             const char* a2 = last ? nA : cA + (size_t)(t + 2) * kstep; const char* b2 = last ? nB : cB + (size_t)(t + 2) * kstep;
;             const char* a3 = a2 + kstep; const char* b3 = b2 + kstep;
;             if (last && has_next) S.a_ready(nxt);
;             PG8_LDB(B0, 0, 0); PG8_SCHED; PG8_LDA(At, 0, 0); PG8_STAGE(PG8_SA(1, 1), a1 + hstep, voffA);
;             PG8_WAIT_L(8); PG8_BAR; PG8_WAIT_L(0); PG8_MMA(0, 0, At, B0); PG8_BAR; PG8_SCHED;
;             PG8_LDB(B1, 0, 1); PG8_STAGE(PG8_SB(0, 0), b2, voffB);
;             PG8_BAR; PG8_WAIT_L(0); PG8_MMA(0, 1, At, B1); PG8_BAR;
;             PG8_LDA(At, 0, 1); PG8_STAGE(PG8_SA(0, 0), a2, voffA);
;             PG8_BAR; PG8_WAIT_L(0); PG8_MMA(1, 0, At, B0); PG8_BAR; PG8_SCHED;
.LBB0_136:
	v_mov_b64_e32 v[0:1], 0x100
	s_ashr_i32 s7, s6, 31
	v_cmp_lt_i64_e32 vcc, s[8:9], v[0:1]
	s_lshl_b64 s[8:9], s[6:7], 19
	s_add_u32 s8, s94, s8
	s_addc_u32 s9, s95, s9
	s_and_b64 s[10:11], vcc, exec
	s_cselect_b32 s7, s9, s13
	s_cselect_b32 s40, s8, s12
	s_ashr_i32 s5, s4, 31
	s_lshl_b64 s[10:11], s[4:5], 19
	v_readlane_b32 s16, v253, 10
	v_readlane_b32 s17, v253, 11
	s_add_u32 s10, s16, s10
	s_addc_u32 s11, s17, s11
	s_and_b64 s[16:17], vcc, exec
	s_cselect_b32 s5, s11, s15
	s_cselect_b32 s41, s10, s14
	s_add_u32 s12, s12, 0x40080
	s_addc_u32 s13, s13, 0
	s_add_u32 s43, s14, 0x100
	s_addc_u32 s44, s15, 0
	s_mov_b32 s45, -2
	s_add_u32 s14, s12, 0xfffc0080
	s_addc_u32 s15, s13, -1
	v_add_u32_e32 v154, 0x10000, v139
	ds_read_b128 v[142:145], v154
	ds_read_b128 v[146:149], v154 offset:1024
	ds_read_b128 v[150:153], v154 offset:2048
	ds_read_b128 v[154:157], v154 offset:3072
	s_cmp_eq_u32 s45, 12
	s_cselect_b32 s17, s7, s15
	s_cselect_b32 s16, s40, s14
	s_cselect_b32 s15, s5, s44
	s_cselect_b32 s14, s41, s43
	s_add_i32 m0, s1, 0xc000
	ds_read_b128 v[158:161], v141
	ds_read_b128 v[162:165], v141 offset:1024
	ds_read_b128 v[166:169], v141 offset:2048
	ds_read_b128 v[170:173], v141 offset:3072
	ds_read_b128 v[178:181], v141 offset:4096
	ds_read_b128 v[182:185], v141 offset:5120
	ds_read_b128 v[186:189], v141 offset:6144
	global_load_lds_dwordx4 v134, s[12:13]
	s_add_i32 m0, s1, 0xe000
	ds_read_b128 v[190:193], v141 offset:7168
	global_load_lds_dwordx4 v136, s[12:13]
	s_waitcnt lgkmcnt(8)
	s_barrier
	s_waitcnt lgkmcnt(7)
	v_mfma_f32_16x16x32_bf16 v[124:127], v[142:145], v[158:161], 0
	v_mfma_f32_16x16x32_bf16 v[120:123], v[150:153], v[158:161], 0
	s_waitcnt lgkmcnt(5)
	v_mfma_f32_16x16x32_bf16 v[116:119], v[142:145], v[166:169], 0
	v_mfma_f32_16x16x32_bf16 v[112:115], v[150:153], v[166:169], 0
	s_waitcnt lgkmcnt(3)
	v_mfma_f32_16x16x32_bf16 v[100:103], v[142:145], v[178:181], 0
	v_mfma_f32_16x16x32_bf16 v[96:99], v[150:153], v[178:181], 0
	s_waitcnt lgkmcnt(1)
	v_mfma_f32_16x16x32_bf16 v[84:87], v[142:145], v[186:189], 0
	v_mfma_f32_16x16x32_bf16 v[80:83], v[150:153], v[186:189], 0
	v_mfma_f32_16x16x32_bf16 v[124:127], v[146:149], v[162:165], v[124:127]
	v_mfma_f32_16x16x32_bf16 v[120:123], v[154:157], v[162:165], v[120:123]
	v_mfma_f32_16x16x32_bf16 v[116:119], v[146:149], v[170:173], v[116:119]
	v_mfma_f32_16x16x32_bf16 v[112:115], v[154:157], v[170:173], v[112:115]
	v_mfma_f32_16x16x32_bf16 v[100:103], v[146:149], v[182:185], v[100:103]
	v_mfma_f32_16x16x32_bf16 v[96:99], v[154:157], v[182:185], v[96:99]
	s_waitcnt lgkmcnt(0)
	v_mfma_f32_16x16x32_bf16 v[84:87], v[146:149], v[190:193], v[84:87]
	v_mfma_f32_16x16x32_bf16 v[80:83], v[154:157], v[190:193], v[80:83]
	s_barrier
	s_add_i32 s48, 0, 0x14000
	v_add_u32_e32 v174, 0x14000, v139
	ds_read_b128 v[194:197], v174
	ds_read_b128 v[198:201], v174 offset:1024
	s_add_u32 s98, s14, 0x80
	s_addc_u32 s99, s15, 0
	s_add_i32 m0, s20, 0x10000
	ds_read_b128 v[202:205], v174 offset:2048
	global_load_lds_dwordx4 v176, s[14:15]
	s_add_i32 m0, s20, 0x12000
	ds_read_b128 v[206:209], v174 offset:3072
	global_load_lds_dwordx4 v128, s[14:15]
	s_barrier
	s_waitcnt lgkmcnt(3)
	v_mfma_f32_16x16x32_bf16 v[108:111], v[194:197], v[158:161], 0
	s_waitcnt lgkmcnt(1)
	v_mfma_f32_16x16x32_bf16 v[104:107], v[202:205], v[158:161], 0
	v_mfma_f32_16x16x32_bf16 v[92:95], v[194:197], v[166:169], 0
	v_mfma_f32_16x16x32_bf16 v[88:91], v[202:205], v[166:169], 0
	v_mfma_f32_16x16x32_bf16 v[76:79], v[194:197], v[178:181], 0
	v_mfma_f32_16x16x32_bf16 v[72:75], v[202:205], v[178:181], 0
	v_mfma_f32_16x16x32_bf16 v[68:71], v[194:197], v[186:189], 0
	v_mfma_f32_16x16x32_bf16 v[64:67], v[202:205], v[186:189], 0
	v_mfma_f32_16x16x32_bf16 v[108:111], v[198:201], v[162:165], v[108:111]
	s_waitcnt lgkmcnt(0)
	v_mfma_f32_16x16x32_bf16 v[104:107], v[206:209], v[162:165], v[104:107]
	v_mfma_f32_16x16x32_bf16 v[92:95], v[198:201], v[170:173], v[92:95]
	v_mfma_f32_16x16x32_bf16 v[88:91], v[206:209], v[170:173], v[88:91]
	v_mfma_f32_16x16x32_bf16 v[76:79], v[198:201], v[182:185], v[76:79]
	v_mfma_f32_16x16x32_bf16 v[72:75], v[206:209], v[182:185], v[72:75]
	v_mfma_f32_16x16x32_bf16 v[68:71], v[198:201], v[190:193], v[68:71]
	v_mfma_f32_16x16x32_bf16 v[64:67], v[206:209], v[190:193], v[64:67]
	s_mov_b32 m0, s1
	s_add_u32 s100, s16, 0x80
	s_addc_u32 s101, s17, 0
	s_barrier
	ds_read_b128 v[158:161], v141 offset:16384
	ds_read_b128 v[162:165], v141 offset:17408
	ds_read_b128 v[166:169], v141 offset:18432
	ds_read_b128 v[170:173], v141 offset:19456
	ds_read_b128 v[178:181], v141 offset:20480
	ds_read_b128 v[182:185], v141 offset:21504
	ds_read_b128 v[186:189], v141 offset:22528
	global_load_lds_dwordx4 v132, s[16:17]
	s_mov_b32 m0, s22
	ds_read_b128 v[190:193], v141 offset:23552
	global_load_lds_dwordx4 v130, s[16:17]
	s_barrier
	s_waitcnt lgkmcnt(7)
	v_mfma_f32_16x16x32_bf16 v[60:63], v[142:145], v[158:161], 0
	v_mfma_f32_16x16x32_bf16 v[56:59], v[150:153], v[158:161], 0
	s_waitcnt lgkmcnt(5)
	v_mfma_f32_16x16x32_bf16 v[52:55], v[142:145], v[166:169], 0
	v_mfma_f32_16x16x32_bf16 v[48:51], v[150:153], v[166:169], 0
	s_waitcnt lgkmcnt(3)
	v_mfma_f32_16x16x32_bf16 v[36:39], v[142:145], v[178:181], 0
	v_mfma_f32_16x16x32_bf16 v[32:35], v[150:153], v[178:181], 0
	s_waitcnt lgkmcnt(1)
	v_mfma_f32_16x16x32_bf16 v[20:23], v[142:145], v[186:189], 0
	v_mfma_f32_16x16x32_bf16 v[16:19], v[150:153], v[186:189], 0
	v_mfma_f32_16x16x32_bf16 v[60:63], v[146:149], v[162:165], v[60:63]
	v_mfma_f32_16x16x32_bf16 v[56:59], v[154:157], v[162:165], v[56:59]
	v_mfma_f32_16x16x32_bf16 v[52:55], v[146:149], v[170:173], v[52:55]
	v_mfma_f32_16x16x32_bf16 v[48:51], v[154:157], v[170:173], v[48:51]
	v_mfma_f32_16x16x32_bf16 v[36:39], v[146:149], v[182:185], v[36:39]
	v_mfma_f32_16x16x32_bf16 v[32:35], v[154:157], v[182:185], v[32:35]
	s_waitcnt lgkmcnt(0)
	v_mfma_f32_16x16x32_bf16 v[20:23], v[146:149], v[190:193], v[20:23]
	v_mfma_f32_16x16x32_bf16 v[16:19], v[154:157], v[190:193], v[16:19]
	s_barrier
; #define PG8_STAGE(bufoff, gbase, voff) do { _Pragma("unroll") for (int _i = 0; _i < 2; ++_i) \
;         __builtin_amdgcn_global_load_lds((const unsigned*)((const char*)(gbase) + (voff)[_i]), (PG8_LAS unsigned*)(lds + (bufoff) + ldsw + _i * 8192), 16, 0, 0); } while (0)
; #define PG8_LDA(dst, b, h) do { _Pragma("unroll") for (int m = 0; m < 4; ++m) _Pragma("unroll") for (int k = 0; k < 2; ++k) dst[m][k] = *(const PG8_LAS bf16x8*)(lds + PG8_SA(b, h) + aoff + m * 2048 + k * 1024); } while (0)
; #define PG8_LDB(dst, b, h) do { _Pragma("unroll") for (int n = 0; n < 2; ++n) _Pragma("unroll") for (int k = 0; k < 2; ++k) dst[n][k] = *(const PG8_LAS bf16x8*)(lds + PG8_SB(b, h) + boff + n * 2048 + k * 1024); } while (0)
; #define PG8_MMA(ai, bj, At, Bt) do { __builtin_amdgcn_s_setprio(1); _Pragma("unroll") for (int m = 0; m < 4; ++m) _Pragma("unroll") for (int n = 0; n < 2; ++n) _Pragma("unroll") for (int k = 0; k < 2; ++k) \
;         acc[ai][bj][m][n] = __builtin_amdgcn_mfma_f32_16x16x32_bf16(Bt[n][k], At[m][k], acc[ai][bj][m][n], 0, 0, 0); __builtin_amdgcn_s_setprio(0); } while (0)
; #define PG8_WAIT_V(n) asm volatile("s_waitcnt vmcnt(" #n ")" ::: "memory")
; #define PG8_WAIT_L(n) asm volatile("s_waitcnt lgkmcnt(" #n ")" ::: "memory")
; #define PG8_BAR __builtin_amdgcn_s_barrier()
; #define PG8_SCHED __builtin_amdgcn_sched_barrier(0)
; template <class Epi, class Sched>
; __device__ __forceinline__ void gemm_phase(PG8_LAS unsigned char* lds, const Gemm g, const Sched& S, const Epi& E) {
;     ...
;             PG8_BAR; PG8_WAIT_L(0); PG8_MMA(1, 0, At, B0); PG8_BAR; PG8_SCHED;
;             PG8_STAGE(PG8_SB(0, 1), b2 + hstep, voffB);
;             PG8_WAIT_V(6); PG8_BAR; PG8_MMA(1, 1, At, B1); PG8_BAR;
;             PG8_LDB(B0, 1, 0); PG8_SCHED; PG8_LDA(At, 1, 0); PG8_STAGE(PG8_SA(0, 1), a2 + hstep, voffA);
;             PG8_WAIT_L(8); PG8_BAR; PG8_WAIT_L(0); PG8_MMA(0, 0, At, B0); PG8_BAR; PG8_SCHED;
;             PG8_LDB(B1, 1, 1); PG8_STAGE(PG8_SB(1, 0), b3, voffB);
;             PG8_BAR; PG8_WAIT_L(0); PG8_MMA(0, 1, At, B1); PG8_BAR;
	s_add_u32 s46, s14, 0x40000
	s_addc_u32 s47, s15, 0
	s_add_i32 m0, s20, 0x14000
	s_nop 0
	global_load_lds_dwordx4 v176, s[46:47]
	s_add_i32 m0, s20, 0x16000
	s_nop 0
	global_load_lds_dwordx4 v128, s[46:47]
	s_waitcnt vmcnt(6)
	s_barrier
	v_mfma_f32_16x16x32_bf16 v[44:47], v[194:197], v[158:161], 0
	v_mfma_f32_16x16x32_bf16 v[40:43], v[202:205], v[158:161], 0
	v_mfma_f32_16x16x32_bf16 v[28:31], v[194:197], v[166:169], 0
	v_mfma_f32_16x16x32_bf16 v[24:27], v[202:205], v[166:169], 0
	v_mfma_f32_16x16x32_bf16 v[12:15], v[194:197], v[178:181], 0
	v_mfma_f32_16x16x32_bf16 v[8:11], v[202:205], v[178:181], 0
	v_mfma_f32_16x16x32_bf16 v[4:7], v[194:197], v[186:189], 0
	v_mfma_f32_16x16x32_bf16 v[0:3], v[202:205], v[186:189], 0
	v_mfma_f32_16x16x32_bf16 v[44:47], v[198:201], v[162:165], v[44:47]
	v_mfma_f32_16x16x32_bf16 v[40:43], v[206:209], v[162:165], v[40:43]
	v_mfma_f32_16x16x32_bf16 v[28:31], v[198:201], v[170:173], v[28:31]
	v_mfma_f32_16x16x32_bf16 v[24:27], v[206:209], v[170:173], v[24:27]
	v_mfma_f32_16x16x32_bf16 v[12:15], v[198:201], v[182:185], v[12:15]
	v_mfma_f32_16x16x32_bf16 v[8:11], v[206:209], v[182:185], v[8:11]
	v_mfma_f32_16x16x32_bf16 v[4:7], v[198:201], v[190:193], v[4:7]
	v_mfma_f32_16x16x32_bf16 v[0:3], v[206:209], v[190:193], v[0:3]
	v_add_u32_e32 v154, 0x18000, v139
	s_barrier
	ds_read_b128 v[142:145], v154
	ds_read_b128 v[146:149], v154 offset:1024
	ds_read_b128 v[150:153], v154 offset:2048
	ds_read_b128 v[154:157], v154 offset:3072
	s_add_u32 s16, s16, 0x40000
	s_addc_u32 s17, s17, 0
	s_mov_b32 m0, s23
	ds_read_b128 v[158:161], v141 offset:32768
	ds_read_b128 v[162:165], v141 offset:33792
	ds_read_b128 v[166:169], v141 offset:34816
	ds_read_b128 v[170:173], v141 offset:35840
	ds_read_b128 v[178:181], v141 offset:36864
	ds_read_b128 v[182:185], v141 offset:37888
	ds_read_b128 v[186:189], v141 offset:38912
	global_load_lds_dwordx4 v132, s[16:17]
	s_mov_b32 m0, s26
	ds_read_b128 v[190:193], v141 offset:39936
	global_load_lds_dwordx4 v130, s[16:17]
	s_waitcnt lgkmcnt(8)
	s_barrier
	s_waitcnt lgkmcnt(7)
	v_mfma_f32_16x16x32_bf16 v[124:127], v[142:145], v[158:161], v[124:127]
	v_mfma_f32_16x16x32_bf16 v[120:123], v[150:153], v[158:161], v[120:123]
	s_waitcnt lgkmcnt(5)
	v_mfma_f32_16x16x32_bf16 v[116:119], v[142:145], v[166:169], v[116:119]
	v_mfma_f32_16x16x32_bf16 v[112:115], v[150:153], v[166:169], v[112:115]
	s_waitcnt lgkmcnt(3)
	v_mfma_f32_16x16x32_bf16 v[100:103], v[142:145], v[178:181], v[100:103]
	v_mfma_f32_16x16x32_bf16 v[96:99], v[150:153], v[178:181], v[96:99]
	s_waitcnt lgkmcnt(1)
	v_mfma_f32_16x16x32_bf16 v[84:87], v[142:145], v[186:189], v[84:87]
	v_mfma_f32_16x16x32_bf16 v[80:83], v[150:153], v[186:189], v[80:83]
	v_mfma_f32_16x16x32_bf16 v[124:127], v[146:149], v[162:165], v[124:127]
	v_mfma_f32_16x16x32_bf16 v[120:123], v[154:157], v[162:165], v[120:123]
	v_mfma_f32_16x16x32_bf16 v[116:119], v[146:149], v[170:173], v[116:119]
	v_mfma_f32_16x16x32_bf16 v[112:115], v[154:157], v[170:173], v[112:115]
	v_mfma_f32_16x16x32_bf16 v[100:103], v[146:149], v[182:185], v[100:103]
	v_mfma_f32_16x16x32_bf16 v[96:99], v[154:157], v[182:185], v[96:99]
	s_waitcnt lgkmcnt(0)
	v_mfma_f32_16x16x32_bf16 v[84:87], v[146:149], v[190:193], v[84:87]
	v_mfma_f32_16x16x32_bf16 v[80:83], v[154:157], v[190:193], v[80:83]
	s_barrier
	v_add_u32_e32 v206, 0x1c000, v139
	s_add_i32 m0, s20, 0x18000
	ds_read_b128 v[194:197], v206
	ds_read_b128 v[198:201], v206 offset:1024
	ds_read_b128 v[202:205], v206 offset:2048
	global_load_lds_dwordx4 v176, s[98:99]
	s_add_i32 m0, s20, 0x1a000
	ds_read_b128 v[206:209], v206 offset:3072
	global_load_lds_dwordx4 v128, s[98:99]
	s_barrier
; #define PG8_STAGE(bufoff, gbase, voff) do { _Pragma("unroll") for (int _i = 0; _i < 2; ++_i) \
;         __builtin_amdgcn_global_load_lds((const unsigned*)((const char*)(gbase) + (voff)[_i]), (PG8_LAS unsigned*)(lds + (bufoff) + ldsw + _i * 8192), 16, 0, 0); } while (0)
; #define PG8_LDA(dst, b, h) do { _Pragma("unroll") for (int m = 0; m < 4; ++m) _Pragma("unroll") for (int k = 0; k < 2; ++k) dst[m][k] = *(const PG8_LAS bf16x8*)(lds + PG8_SA(b, h) + aoff + m * 2048 + k * 1024); } while (0)
; #define PG8_MMA(ai, bj, At, Bt) do { __builtin_amdgcn_s_setprio(1); _Pragma("unroll") for (int m = 0; m < 4; ++m) _Pragma("unroll") for (int n = 0; n < 2; ++n) _Pragma("unroll") for (int k = 0; k < 2; ++k) \
;         acc[ai][bj][m][n] = __builtin_amdgcn_mfma_f32_16x16x32_bf16(Bt[n][k], At[m][k], acc[ai][bj][m][n], 0, 0, 0); __builtin_amdgcn_s_setprio(0); } while (0)
; #define PG8_WAIT_V(n) asm volatile("s_waitcnt vmcnt(" #n ")" ::: "memory")
; #define PG8_WAIT_L(n) asm volatile("s_waitcnt lgkmcnt(" #n ")" ::: "memory")
; #define PG8_BAR __builtin_amdgcn_s_barrier()
; #define PG8_SCHED __builtin_amdgcn_sched_barrier(0)
; template <class Epi, class Sched>
; __device__ __forceinline__ void gemm_phase(PG8_LAS unsigned char* lds, const Gemm g, const Sched& S, const Epi& E) {
;     ...
;             PG8_BAR; PG8_WAIT_L(0); PG8_MMA(0, 1, At, B1); PG8_BAR;
;             PG8_LDA(At, 1, 1); PG8_STAGE(PG8_SA(1, 0), a3, voffA);
;             PG8_BAR; PG8_WAIT_L(0); PG8_MMA(1, 0, At, B0); PG8_BAR; PG8_SCHED;
;             PG8_STAGE(PG8_SB(1, 1), b3 + hstep, voffB);
;             PG8_WAIT_V(6); PG8_BAR; PG8_MMA(1, 1, At, B1); PG8_BAR;
;         }
	s_waitcnt lgkmcnt(3)
	v_mfma_f32_16x16x32_bf16 v[108:111], v[194:197], v[158:161], v[108:111]
	s_waitcnt lgkmcnt(1)
	v_mfma_f32_16x16x32_bf16 v[104:107], v[202:205], v[158:161], v[104:107]
	v_mfma_f32_16x16x32_bf16 v[92:95], v[194:197], v[166:169], v[92:95]
	v_mfma_f32_16x16x32_bf16 v[88:91], v[202:205], v[166:169], v[88:91]
	v_mfma_f32_16x16x32_bf16 v[76:79], v[194:197], v[178:181], v[76:79]
	v_mfma_f32_16x16x32_bf16 v[72:75], v[202:205], v[178:181], v[72:75]
	v_mfma_f32_16x16x32_bf16 v[68:71], v[194:197], v[186:189], v[68:71]
	v_mfma_f32_16x16x32_bf16 v[64:67], v[202:205], v[186:189], v[64:67]
	v_mfma_f32_16x16x32_bf16 v[108:111], v[198:201], v[162:165], v[108:111]
	s_waitcnt lgkmcnt(0)
	v_mfma_f32_16x16x32_bf16 v[104:107], v[206:209], v[162:165], v[104:107]
	v_mfma_f32_16x16x32_bf16 v[92:95], v[198:201], v[170:173], v[92:95]
	v_mfma_f32_16x16x32_bf16 v[88:91], v[206:209], v[170:173], v[88:91]
	v_mfma_f32_16x16x32_bf16 v[76:79], v[198:201], v[182:185], v[76:79]
	v_mfma_f32_16x16x32_bf16 v[72:75], v[206:209], v[182:185], v[72:75]
	v_mfma_f32_16x16x32_bf16 v[68:71], v[198:201], v[190:193], v[68:71]
	v_mfma_f32_16x16x32_bf16 v[64:67], v[206:209], v[190:193], v[64:67]
	s_mov_b32 m0, s28
	s_barrier
	ds_read_b128 v[158:161], v141 offset:49152
	ds_read_b128 v[162:165], v141 offset:50176
	ds_read_b128 v[166:169], v141 offset:51200
	ds_read_b128 v[170:173], v141 offset:52224
	ds_read_b128 v[178:181], v141 offset:53248
	ds_read_b128 v[182:185], v141 offset:54272
	ds_read_b128 v[186:189], v141 offset:55296
	global_load_lds_dwordx4 v132, s[100:101]
	s_mov_b32 m0, s29
	ds_read_b128 v[190:193], v141 offset:56320
	global_load_lds_dwordx4 v130, s[100:101]
	s_barrier
	s_waitcnt lgkmcnt(7)
	v_mfma_f32_16x16x32_bf16 v[60:63], v[142:145], v[158:161], v[60:63]
	v_mfma_f32_16x16x32_bf16 v[56:59], v[150:153], v[158:161], v[56:59]
	s_waitcnt lgkmcnt(5)
	v_mfma_f32_16x16x32_bf16 v[52:55], v[142:145], v[166:169], v[52:55]
	v_mfma_f32_16x16x32_bf16 v[48:51], v[150:153], v[166:169], v[48:51]
	s_waitcnt lgkmcnt(3)
	v_mfma_f32_16x16x32_bf16 v[36:39], v[142:145], v[178:181], v[36:39]
	v_mfma_f32_16x16x32_bf16 v[32:35], v[150:153], v[178:181], v[32:35]
	s_waitcnt lgkmcnt(1)
	v_mfma_f32_16x16x32_bf16 v[20:23], v[142:145], v[186:189], v[20:23]
	v_mfma_f32_16x16x32_bf16 v[16:19], v[150:153], v[186:189], v[16:19]
	v_mfma_f32_16x16x32_bf16 v[60:63], v[146:149], v[162:165], v[60:63]
	v_mfma_f32_16x16x32_bf16 v[56:59], v[154:157], v[162:165], v[56:59]
	v_mfma_f32_16x16x32_bf16 v[52:55], v[146:149], v[170:173], v[52:55]
	v_mfma_f32_16x16x32_bf16 v[48:51], v[154:157], v[170:173], v[48:51]
	v_mfma_f32_16x16x32_bf16 v[36:39], v[146:149], v[182:185], v[36:39]
	v_mfma_f32_16x16x32_bf16 v[32:35], v[154:157], v[182:185], v[32:35]
	s_waitcnt lgkmcnt(0)
	v_mfma_f32_16x16x32_bf16 v[20:23], v[146:149], v[190:193], v[20:23]
	v_mfma_f32_16x16x32_bf16 v[16:19], v[154:157], v[190:193], v[16:19]
	s_barrier
	s_add_u32 s14, s14, 0x40080
	s_addc_u32 s15, s15, 0
	s_add_i32 m0, s20, 0x1c000
	s_nop 0
	global_load_lds_dwordx4 v176, s[14:15]
	s_add_i32 m0, s20, 0x1e000
	s_nop 0
	global_load_lds_dwordx4 v128, s[14:15]
	s_waitcnt vmcnt(6)
	s_barrier
	v_mfma_f32_16x16x32_bf16 v[44:47], v[194:197], v[158:161], v[44:47]
	v_mfma_f32_16x16x32_bf16 v[40:43], v[202:205], v[158:161], v[40:43]
	v_mfma_f32_16x16x32_bf16 v[28:31], v[194:197], v[166:169], v[28:31]
	v_mfma_f32_16x16x32_bf16 v[24:27], v[202:205], v[166:169], v[24:27]
	v_mfma_f32_16x16x32_bf16 v[12:15], v[194:197], v[178:181], v[12:15]
	v_mfma_f32_16x16x32_bf16 v[8:11], v[202:205], v[178:181], v[8:11]
	v_mfma_f32_16x16x32_bf16 v[4:7], v[194:197], v[186:189], v[4:7]
	v_mfma_f32_16x16x32_bf16 v[0:3], v[202:205], v[186:189], v[0:3]
	v_mfma_f32_16x16x32_bf16 v[44:47], v[198:201], v[162:165], v[44:47]
	v_mfma_f32_16x16x32_bf16 v[40:43], v[206:209], v[162:165], v[40:43]
	v_mfma_f32_16x16x32_bf16 v[28:31], v[198:201], v[170:173], v[28:31]
	v_mfma_f32_16x16x32_bf16 v[24:27], v[206:209], v[170:173], v[24:27]
	v_mfma_f32_16x16x32_bf16 v[12:15], v[198:201], v[182:185], v[12:15]
	v_mfma_f32_16x16x32_bf16 v[8:11], v[206:209], v[182:185], v[8:11]
	v_mfma_f32_16x16x32_bf16 v[4:7], v[198:201], v[190:193], v[4:7]
	v_mfma_f32_16x16x32_bf16 v[0:3], v[206:209], v[190:193], v[0:3]
	s_add_i32 s45, s45, 2
	s_add_u32 s12, s12, 0x100
	s_addc_u32 s13, s13, 0
	s_add_u32 s43, s43, 0x100
	s_addc_u32 s44, s44, 0
	s_cmp_gt_u32 s45, 13
	s_barrier

; #define PG8_STAGE(bufoff, gbase, voff) do { _Pragma("unroll") for (int _i = 0; _i < 2; ++_i) \
;         __builtin_amdgcn_global_load_lds((const unsigned*)((const char*)(gbase) + (voff)[_i]), (PG8_LAS unsigned*)(lds + (bufoff) + ldsw + _i * 8192), 16, 0, 0); } while (0)
; #define PG8_LDA(dst, b, h) do { _Pragma("unroll") for (int m = 0; m < 4; ++m) _Pragma("unroll") for (int k = 0; k < 2; ++k) dst[m][k] = *(const PG8_LAS bf16x8*)(lds + PG8_SA(b, h) + aoff + m * 2048 + k * 1024); } while (0)
; #define PG8_LDB(dst, b, h) do { _Pragma("unroll") for (int n = 0; n < 2; ++n) _Pragma("unroll") for (int k = 0; k < 2; ++k) dst[n][k] = *(const PG8_LAS bf16x8*)(lds + PG8_SB(b, h) + boff + n * 2048 + k * 1024); } while (0)
; #define PG8_MMA(ai, bj, At, Bt) do { __builtin_amdgcn_s_setprio(1); _Pragma("unroll") for (int m = 0; m < 4; ++m) _Pragma("unroll") for (int n = 0; n < 2; ++n) _Pragma("unroll") for (int k = 0; k < 2; ++k) \
;         acc[ai][bj][m][n] = __builtin_amdgcn_mfma_f32_16x16x32_bf16(Bt[n][k], At[m][k], acc[ai][bj][m][n], 0, 0, 0); __builtin_amdgcn_s_setprio(0); } while (0)
; template <class Epi, class Sched>
; __device__ __forceinline__ void gemm_phase(PG8_LAS unsigned char* lds, const Gemm g, const Sched& S, const Epi& E) {
;     ...
;         const bool has_next = S.next(ui + 1, nxt);
;         const char* nA = has_next ? (const char*)g.A + (size_t)nxt.pm * tstep : cA; const char* nB = has_next ? (const char*)g.Bt + (size_t)nxt.pn * tstep : cB;
;         for (int t = 0; t < nt; t += 2) {
;             const bool last = (t == nt - 2);
;             const char* a1 = cA + (size_t)(t + 1) * kstep;
;             const char* a2 = last ? nA : cA + (size_t)(t + 2) * kstep; const char* b2 = last ? nB : cB + (size_t)(t + 2) * kstep;
;             const char* a3 = a2 + kstep; const char* b3 = b2 + kstep;
;             if (last && has_next) S.a_ready(nxt);
;             PG8_LDB(B0, 0, 0); PG8_SCHED; PG8_LDA(At, 0, 0); PG8_STAGE(PG8_SA(1, 1), a1 + hstep, voffA);
;             PG8_WAIT_L(8); PG8_BAR; PG8_WAIT_L(0); PG8_MMA(0, 0, At, B0); PG8_BAR; PG8_SCHED;
;             PG8_LDB(B1, 0, 1); PG8_STAGE(PG8_SB(0, 0), b2, voffB);
;             PG8_BAR; PG8_WAIT_L(0); PG8_MMA(0, 1, At, B1); PG8_BAR;
;             PG8_LDA(At, 0, 1); PG8_STAGE(PG8_SA(0, 0), a2, voffA);
;             PG8_BAR; PG8_WAIT_L(0); PG8_MMA(1, 0, At, B0); PG8_BAR; PG8_SCHED;
.LBB0_357:
	v_mov_b64_e32 v[0:1], 0x2c0
	s_ashr_i32 s7, s6, 31
	v_cmp_lt_i64_e32 vcc, s[8:9], v[0:1]
	s_lshl_b64 s[8:9], s[6:7], 19
	s_add_u32 s8, s94, s8
	s_addc_u32 s9, s95, s9
	s_and_b64 s[10:11], vcc, exec
	s_cselect_b32 s7, s9, s13
	s_cselect_b32 s40, s8, s12
	s_ashr_i32 s5, s4, 31
	s_lshl_b64 s[10:11], s[4:5], 19
	s_add_u32 s10, s92, s10
	s_addc_u32 s11, s93, s11
	s_and_b64 s[16:17], vcc, exec
	s_cselect_b32 s5, s11, s15
	s_cselect_b32 s41, s10, s14
	s_add_u32 s12, s12, 0x40080
	s_addc_u32 s13, s13, 0
	s_add_u32 s43, s14, 0x100
	s_addc_u32 s44, s15, 0
	s_mov_b32 s45, -2
	s_add_u32 s14, s12, 0xfffc0080
	s_addc_u32 s15, s13, -1
	v_add_u32_e32 v154, 0x10000, v139
	ds_read_b128 v[142:145], v154
	ds_read_b128 v[146:149], v154 offset:1024
	ds_read_b128 v[150:153], v154 offset:2048
	ds_read_b128 v[154:157], v154 offset:3072
	s_cmp_eq_u32 s45, 12
	s_cselect_b32 s17, s7, s15
	s_cselect_b32 s16, s40, s14
	s_cselect_b32 s15, s5, s44
	s_cselect_b32 s14, s41, s43
	s_add_i32 m0, s1, 0xc000
	ds_read_b128 v[158:161], v141
	ds_read_b128 v[162:165], v141 offset:1024
	ds_read_b128 v[166:169], v141 offset:2048
	ds_read_b128 v[170:173], v141 offset:3072
	ds_read_b128 v[182:185], v141 offset:4096
	ds_read_b128 v[190:193], v141 offset:5120
	ds_read_b128 v[194:197], v141 offset:6144
	global_load_lds_dwordx4 v134, s[12:13]
	s_add_i32 m0, s1, 0xe000
	ds_read_b128 v[198:201], v141 offset:7168
	global_load_lds_dwordx4 v136, s[12:13]
	s_waitcnt lgkmcnt(8)
	s_barrier
	s_waitcnt lgkmcnt(7)
	v_mfma_f32_16x16x32_bf16 v[124:127], v[142:145], v[158:161], 0
	v_mfma_f32_16x16x32_bf16 v[120:123], v[150:153], v[158:161], 0
	s_waitcnt lgkmcnt(5)
	v_mfma_f32_16x16x32_bf16 v[116:119], v[142:145], v[166:169], 0
	v_mfma_f32_16x16x32_bf16 v[112:115], v[150:153], v[166:169], 0
	s_waitcnt lgkmcnt(3)
	v_mfma_f32_16x16x32_bf16 v[100:103], v[142:145], v[182:185], 0
	v_mfma_f32_16x16x32_bf16 v[96:99], v[150:153], v[182:185], 0
	s_waitcnt lgkmcnt(1)
	v_mfma_f32_16x16x32_bf16 v[84:87], v[142:145], v[194:197], 0
	v_mfma_f32_16x16x32_bf16 v[80:83], v[150:153], v[194:197], 0
	v_mfma_f32_16x16x32_bf16 v[124:127], v[146:149], v[162:165], v[124:127]
	v_mfma_f32_16x16x32_bf16 v[120:123], v[154:157], v[162:165], v[120:123]
	v_mfma_f32_16x16x32_bf16 v[116:119], v[146:149], v[170:173], v[116:119]
	v_mfma_f32_16x16x32_bf16 v[112:115], v[154:157], v[170:173], v[112:115]
	v_mfma_f32_16x16x32_bf16 v[100:103], v[146:149], v[190:193], v[100:103]
	v_mfma_f32_16x16x32_bf16 v[96:99], v[154:157], v[190:193], v[96:99]
	s_waitcnt lgkmcnt(0)
	v_mfma_f32_16x16x32_bf16 v[84:87], v[146:149], v[198:201], v[84:87]
	v_mfma_f32_16x16x32_bf16 v[80:83], v[154:157], v[198:201], v[80:83]
	s_barrier
	s_add_i32 s48, 0, 0x14000
	v_add_u32_e32 v174, 0x14000, v139
	ds_read_b128 v[202:205], v174
	ds_read_b128 v[206:209], v174 offset:1024
	s_add_u32 s98, s14, 0x80
	s_addc_u32 s99, s15, 0
	s_add_i32 m0, s20, 0x10000
	ds_read_b128 v[210:213], v174 offset:2048
	global_load_lds_dwordx4 v176, s[14:15]
	s_add_i32 m0, s20, 0x12000
	ds_read_b128 v[214:217], v174 offset:3072
	global_load_lds_dwordx4 v128, s[14:15]
	s_barrier
	s_waitcnt lgkmcnt(3)
	v_mfma_f32_16x16x32_bf16 v[108:111], v[202:205], v[158:161], 0
	s_waitcnt lgkmcnt(1)
	v_mfma_f32_16x16x32_bf16 v[104:107], v[210:213], v[158:161], 0
	v_mfma_f32_16x16x32_bf16 v[92:95], v[202:205], v[166:169], 0
	v_mfma_f32_16x16x32_bf16 v[88:91], v[210:213], v[166:169], 0
	v_mfma_f32_16x16x32_bf16 v[76:79], v[202:205], v[182:185], 0
	v_mfma_f32_16x16x32_bf16 v[72:75], v[210:213], v[182:185], 0
	v_mfma_f32_16x16x32_bf16 v[68:71], v[202:205], v[194:197], 0
	v_mfma_f32_16x16x32_bf16 v[64:67], v[210:213], v[194:197], 0
	v_mfma_f32_16x16x32_bf16 v[108:111], v[206:209], v[162:165], v[108:111]
	s_waitcnt lgkmcnt(0)
	v_mfma_f32_16x16x32_bf16 v[104:107], v[214:217], v[162:165], v[104:107]
	v_mfma_f32_16x16x32_bf16 v[92:95], v[206:209], v[170:173], v[92:95]
	v_mfma_f32_16x16x32_bf16 v[88:91], v[214:217], v[170:173], v[88:91]
	v_mfma_f32_16x16x32_bf16 v[76:79], v[206:209], v[190:193], v[76:79]
	v_mfma_f32_16x16x32_bf16 v[72:75], v[214:217], v[190:193], v[72:75]
	v_mfma_f32_16x16x32_bf16 v[68:71], v[206:209], v[198:201], v[68:71]
	v_mfma_f32_16x16x32_bf16 v[64:67], v[214:217], v[198:201], v[64:67]
	s_mov_b32 m0, s1
	s_add_u32 s100, s16, 0x80
	s_addc_u32 s101, s17, 0
	s_barrier
	ds_read_b128 v[158:161], v141 offset:16384
	ds_read_b128 v[162:165], v141 offset:17408
	ds_read_b128 v[166:169], v141 offset:18432
	ds_read_b128 v[170:173], v141 offset:19456
	ds_read_b128 v[182:185], v141 offset:20480
	ds_read_b128 v[190:193], v141 offset:21504
	ds_read_b128 v[194:197], v141 offset:22528
	global_load_lds_dwordx4 v132, s[16:17]
	s_mov_b32 m0, s22
	ds_read_b128 v[198:201], v141 offset:23552
	global_load_lds_dwordx4 v130, s[16:17]
	s_barrier
	s_waitcnt lgkmcnt(7)
	v_mfma_f32_16x16x32_bf16 v[60:63], v[142:145], v[158:161], 0
	v_mfma_f32_16x16x32_bf16 v[56:59], v[150:153], v[158:161], 0
	s_waitcnt lgkmcnt(5)
	v_mfma_f32_16x16x32_bf16 v[52:55], v[142:145], v[166:169], 0
	v_mfma_f32_16x16x32_bf16 v[48:51], v[150:153], v[166:169], 0
	s_waitcnt lgkmcnt(3)
	v_mfma_f32_16x16x32_bf16 v[36:39], v[142:145], v[182:185], 0
	v_mfma_f32_16x16x32_bf16 v[32:35], v[150:153], v[182:185], 0
	s_waitcnt lgkmcnt(1)
	v_mfma_f32_16x16x32_bf16 v[20:23], v[142:145], v[194:197], 0
	v_mfma_f32_16x16x32_bf16 v[16:19], v[150:153], v[194:197], 0
	v_mfma_f32_16x16x32_bf16 v[60:63], v[146:149], v[162:165], v[60:63]
	v_mfma_f32_16x16x32_bf16 v[56:59], v[154:157], v[162:165], v[56:59]
	v_mfma_f32_16x16x32_bf16 v[52:55], v[146:149], v[170:173], v[52:55]
	v_mfma_f32_16x16x32_bf16 v[48:51], v[154:157], v[170:173], v[48:51]
	v_mfma_f32_16x16x32_bf16 v[36:39], v[146:149], v[190:193], v[36:39]
	v_mfma_f32_16x16x32_bf16 v[32:35], v[154:157], v[190:193], v[32:35]
	s_waitcnt lgkmcnt(0)
	v_mfma_f32_16x16x32_bf16 v[20:23], v[146:149], v[198:201], v[20:23]
	v_mfma_f32_16x16x32_bf16 v[16:19], v[154:157], v[198:201], v[16:19]
	s_barrier
; #define PG8_STAGE(bufoff, gbase, voff) do { _Pragma("unroll") for (int _i = 0; _i < 2; ++_i) \
;         __builtin_amdgcn_global_load_lds((const unsigned*)((const char*)(gbase) + (voff)[_i]), (PG8_LAS unsigned*)(lds + (bufoff) + ldsw + _i * 8192), 16, 0, 0); } while (0)
; #define PG8_LDA(dst, b, h) do { _Pragma("unroll") for (int m = 0; m < 4; ++m) _Pragma("unroll") for (int k = 0; k < 2; ++k) dst[m][k] = *(const PG8_LAS bf16x8*)(lds + PG8_SA(b, h) + aoff + m * 2048 + k * 1024); } while (0)
; #define PG8_LDB(dst, b, h) do { _Pragma("unroll") for (int n = 0; n < 2; ++n) _Pragma("unroll") for (int k = 0; k < 2; ++k) dst[n][k] = *(const PG8_LAS bf16x8*)(lds + PG8_SB(b, h) + boff + n * 2048 + k * 1024); } while (0)
; #define PG8_MMA(ai, bj, At, Bt) do { __builtin_amdgcn_s_setprio(1); _Pragma("unroll") for (int m = 0; m < 4; ++m) _Pragma("unroll") for (int n = 0; n < 2; ++n) _Pragma("unroll") for (int k = 0; k < 2; ++k) \
;         acc[ai][bj][m][n] = __builtin_amdgcn_mfma_f32_16x16x32_bf16(Bt[n][k], At[m][k], acc[ai][bj][m][n], 0, 0, 0); __builtin_amdgcn_s_setprio(0); } while (0)
; #define PG8_WAIT_V(n) asm volatile("s_waitcnt vmcnt(" #n ")" ::: "memory")
; #define PG8_WAIT_L(n) asm volatile("s_waitcnt lgkmcnt(" #n ")" ::: "memory")
; #define PG8_BAR __builtin_amdgcn_s_barrier()
; #define PG8_SCHED __builtin_amdgcn_sched_barrier(0)
; template <class Epi, class Sched>
; __device__ __forceinline__ void gemm_phase(PG8_LAS unsigned char* lds, const Gemm g, const Sched& S, const Epi& E) {
;     ...
;             PG8_STAGE(PG8_SB(0, 1), b2 + hstep, voffB);
;             PG8_WAIT_V(6); PG8_BAR; PG8_MMA(1, 1, At, B1); PG8_BAR;
;             PG8_LDB(B0, 1, 0); PG8_SCHED; PG8_LDA(At, 1, 0); PG8_STAGE(PG8_SA(0, 1), a2 + hstep, voffA);
;             PG8_WAIT_L(8); PG8_BAR; PG8_WAIT_L(0); PG8_MMA(0, 0, At, B0); PG8_BAR; PG8_SCHED;
;             PG8_LDB(B1, 1, 1); PG8_STAGE(PG8_SB(1, 0), b3, voffB);
;             PG8_BAR; PG8_WAIT_L(0); PG8_MMA(0, 1, At, B1); PG8_BAR;
;             PG8_LDA(At, 1, 1); PG8_STAGE(PG8_SA(1, 0), a3, voffA);
	s_add_u32 s46, s14, 0x40000
	s_addc_u32 s47, s15, 0
	s_add_i32 m0, s20, 0x14000
	s_nop 0
	global_load_lds_dwordx4 v176, s[46:47]
	s_add_i32 m0, s20, 0x16000
	s_nop 0
	global_load_lds_dwordx4 v128, s[46:47]
	s_waitcnt vmcnt(6)
	s_barrier
	v_mfma_f32_16x16x32_bf16 v[44:47], v[202:205], v[158:161], 0
	v_mfma_f32_16x16x32_bf16 v[40:43], v[210:213], v[158:161], 0
	v_mfma_f32_16x16x32_bf16 v[28:31], v[202:205], v[166:169], 0
	v_mfma_f32_16x16x32_bf16 v[24:27], v[210:213], v[166:169], 0
	v_mfma_f32_16x16x32_bf16 v[12:15], v[202:205], v[182:185], 0
	v_mfma_f32_16x16x32_bf16 v[8:11], v[210:213], v[182:185], 0
	v_mfma_f32_16x16x32_bf16 v[4:7], v[202:205], v[194:197], 0
	v_mfma_f32_16x16x32_bf16 v[0:3], v[210:213], v[194:197], 0
	v_mfma_f32_16x16x32_bf16 v[44:47], v[206:209], v[162:165], v[44:47]
	v_mfma_f32_16x16x32_bf16 v[40:43], v[214:217], v[162:165], v[40:43]
	v_mfma_f32_16x16x32_bf16 v[28:31], v[206:209], v[170:173], v[28:31]
	v_mfma_f32_16x16x32_bf16 v[24:27], v[214:217], v[170:173], v[24:27]
	v_mfma_f32_16x16x32_bf16 v[12:15], v[206:209], v[190:193], v[12:15]
	v_mfma_f32_16x16x32_bf16 v[8:11], v[214:217], v[190:193], v[8:11]
	v_mfma_f32_16x16x32_bf16 v[4:7], v[206:209], v[198:201], v[4:7]
	v_mfma_f32_16x16x32_bf16 v[0:3], v[214:217], v[198:201], v[0:3]
	v_add_u32_e32 v154, 0x18000, v139
	s_barrier
	ds_read_b128 v[142:145], v154
	ds_read_b128 v[146:149], v154 offset:1024
	ds_read_b128 v[150:153], v154 offset:2048
	ds_read_b128 v[154:157], v154 offset:3072
	s_add_u32 s16, s16, 0x40000
	s_addc_u32 s17, s17, 0
	s_mov_b32 m0, s23
	ds_read_b128 v[158:161], v141 offset:32768
	ds_read_b128 v[162:165], v141 offset:33792
	ds_read_b128 v[166:169], v141 offset:34816
	ds_read_b128 v[170:173], v141 offset:35840
	ds_read_b128 v[182:185], v141 offset:36864
	ds_read_b128 v[190:193], v141 offset:37888
	ds_read_b128 v[194:197], v141 offset:38912
	global_load_lds_dwordx4 v132, s[16:17]
	s_mov_b32 m0, s26
	ds_read_b128 v[198:201], v141 offset:39936
	global_load_lds_dwordx4 v130, s[16:17]
	s_waitcnt lgkmcnt(8)
	s_barrier
	s_waitcnt lgkmcnt(7)
	v_mfma_f32_16x16x32_bf16 v[124:127], v[142:145], v[158:161], v[124:127]
	v_mfma_f32_16x16x32_bf16 v[120:123], v[150:153], v[158:161], v[120:123]
	s_waitcnt lgkmcnt(5)
	v_mfma_f32_16x16x32_bf16 v[116:119], v[142:145], v[166:169], v[116:119]
	v_mfma_f32_16x16x32_bf16 v[112:115], v[150:153], v[166:169], v[112:115]
	s_waitcnt lgkmcnt(3)
	v_mfma_f32_16x16x32_bf16 v[100:103], v[142:145], v[182:185], v[100:103]
	v_mfma_f32_16x16x32_bf16 v[96:99], v[150:153], v[182:185], v[96:99]
	s_waitcnt lgkmcnt(1)
	v_mfma_f32_16x16x32_bf16 v[84:87], v[142:145], v[194:197], v[84:87]
	v_mfma_f32_16x16x32_bf16 v[80:83], v[150:153], v[194:197], v[80:83]
	v_mfma_f32_16x16x32_bf16 v[124:127], v[146:149], v[162:165], v[124:127]
	v_mfma_f32_16x16x32_bf16 v[120:123], v[154:157], v[162:165], v[120:123]
	v_mfma_f32_16x16x32_bf16 v[116:119], v[146:149], v[170:173], v[116:119]
	v_mfma_f32_16x16x32_bf16 v[112:115], v[154:157], v[170:173], v[112:115]
	v_mfma_f32_16x16x32_bf16 v[100:103], v[146:149], v[190:193], v[100:103]
	v_mfma_f32_16x16x32_bf16 v[96:99], v[154:157], v[190:193], v[96:99]
	s_waitcnt lgkmcnt(0)
	v_mfma_f32_16x16x32_bf16 v[84:87], v[146:149], v[198:201], v[84:87]
	v_mfma_f32_16x16x32_bf16 v[80:83], v[154:157], v[198:201], v[80:83]
	s_barrier
	v_add_u32_e32 v188, 0x1c000, v139
	s_add_i32 m0, s20, 0x18000
	ds_read_b128 v[202:205], v188
	ds_read_b128 v[206:209], v188 offset:1024
	ds_read_b128 v[210:213], v188 offset:2048
	global_load_lds_dwordx4 v176, s[98:99]
	s_add_i32 m0, s20, 0x1a000
	ds_read_b128 v[214:217], v188 offset:3072
	global_load_lds_dwordx4 v128, s[98:99]
	s_barrier
; #define PG8_STAGE(bufoff, gbase, voff) do { _Pragma("unroll") for (int _i = 0; _i < 2; ++_i) \
;         __builtin_amdgcn_global_load_lds((const unsigned*)((const char*)(gbase) + (voff)[_i]), (PG8_LAS unsigned*)(lds + (bufoff) + ldsw + _i * 8192), 16, 0, 0); } while (0)
; #define PG8_LDA(dst, b, h) do { _Pragma("unroll") for (int m = 0; m < 4; ++m) _Pragma("unroll") for (int k = 0; k < 2; ++k) dst[m][k] = *(const PG8_LAS bf16x8*)(lds + PG8_SA(b, h) + aoff + m * 2048 + k * 1024); } while (0)
; #define PG8_MMA(ai, bj, At, Bt) do { __builtin_amdgcn_s_setprio(1); _Pragma("unroll") for (int m = 0; m < 4; ++m) _Pragma("unroll") for (int n = 0; n < 2; ++n) _Pragma("unroll") for (int k = 0; k < 2; ++k) \
;         acc[ai][bj][m][n] = __builtin_amdgcn_mfma_f32_16x16x32_bf16(Bt[n][k], At[m][k], acc[ai][bj][m][n], 0, 0, 0); __builtin_amdgcn_s_setprio(0); } while (0)
; #define PG8_WAIT_V(n) asm volatile("s_waitcnt vmcnt(" #n ")" ::: "memory")
; #define PG8_WAIT_L(n) asm volatile("s_waitcnt lgkmcnt(" #n ")" ::: "memory")
; #define PG8_BAR __builtin_amdgcn_s_barrier()
; #define PG8_SCHED __builtin_amdgcn_sched_barrier(0)
; template <class Epi, class Sched>
; __device__ __forceinline__ void gemm_phase(PG8_LAS unsigned char* lds, const Gemm g, const Sched& S, const Epi& E) {
;     ...
;             PG8_BAR; PG8_WAIT_L(0); PG8_MMA(0, 1, At, B1); PG8_BAR;
;             PG8_LDA(At, 1, 1); PG8_STAGE(PG8_SA(1, 0), a3, voffA);
;             PG8_BAR; PG8_WAIT_L(0); PG8_MMA(1, 0, At, B0); PG8_BAR; PG8_SCHED;
;             PG8_STAGE(PG8_SB(1, 1), b3 + hstep, voffB);
;             PG8_WAIT_V(6); PG8_BAR; PG8_MMA(1, 1, At, B1); PG8_BAR;
	s_waitcnt lgkmcnt(3)
	v_mfma_f32_16x16x32_bf16 v[108:111], v[202:205], v[158:161], v[108:111]
	s_waitcnt lgkmcnt(1)
	v_mfma_f32_16x16x32_bf16 v[104:107], v[210:213], v[158:161], v[104:107]
	v_mfma_f32_16x16x32_bf16 v[92:95], v[202:205], v[166:169], v[92:95]
	v_mfma_f32_16x16x32_bf16 v[88:91], v[210:213], v[166:169], v[88:91]
	v_mfma_f32_16x16x32_bf16 v[76:79], v[202:205], v[182:185], v[76:79]
	v_mfma_f32_16x16x32_bf16 v[72:75], v[210:213], v[182:185], v[72:75]
	v_mfma_f32_16x16x32_bf16 v[68:71], v[202:205], v[194:197], v[68:71]
	v_mfma_f32_16x16x32_bf16 v[64:67], v[210:213], v[194:197], v[64:67]
	v_mfma_f32_16x16x32_bf16 v[108:111], v[206:209], v[162:165], v[108:111]
	s_waitcnt lgkmcnt(0)
	v_mfma_f32_16x16x32_bf16 v[104:107], v[214:217], v[162:165], v[104:107]
	v_mfma_f32_16x16x32_bf16 v[92:95], v[206:209], v[170:173], v[92:95]
	v_mfma_f32_16x16x32_bf16 v[88:91], v[214:217], v[170:173], v[88:91]
	v_mfma_f32_16x16x32_bf16 v[76:79], v[206:209], v[190:193], v[76:79]
	v_mfma_f32_16x16x32_bf16 v[72:75], v[214:217], v[190:193], v[72:75]
	v_mfma_f32_16x16x32_bf16 v[68:71], v[206:209], v[198:201], v[68:71]
	v_mfma_f32_16x16x32_bf16 v[64:67], v[214:217], v[198:201], v[64:67]
	s_mov_b32 m0, s28
	s_barrier
	ds_read_b128 v[158:161], v141 offset:49152
	ds_read_b128 v[162:165], v141 offset:50176
	ds_read_b128 v[166:169], v141 offset:51200
	ds_read_b128 v[170:173], v141 offset:52224
	ds_read_b128 v[182:185], v141 offset:53248
	ds_read_b128 v[190:193], v141 offset:54272
	ds_read_b128 v[194:197], v141 offset:55296
	global_load_lds_dwordx4 v132, s[100:101]
	s_mov_b32 m0, s29
	ds_read_b128 v[198:201], v141 offset:56320
	global_load_lds_dwordx4 v130, s[100:101]
	s_barrier
	s_waitcnt lgkmcnt(7)
	v_mfma_f32_16x16x32_bf16 v[60:63], v[142:145], v[158:161], v[60:63]
	v_mfma_f32_16x16x32_bf16 v[56:59], v[150:153], v[158:161], v[56:59]
	s_waitcnt lgkmcnt(5)
	v_mfma_f32_16x16x32_bf16 v[52:55], v[142:145], v[166:169], v[52:55]
	v_mfma_f32_16x16x32_bf16 v[48:51], v[150:153], v[166:169], v[48:51]
	s_waitcnt lgkmcnt(3)
	v_mfma_f32_16x16x32_bf16 v[36:39], v[142:145], v[182:185], v[36:39]
	v_mfma_f32_16x16x32_bf16 v[32:35], v[150:153], v[182:185], v[32:35]
	s_waitcnt lgkmcnt(1)
	v_mfma_f32_16x16x32_bf16 v[20:23], v[142:145], v[194:197], v[20:23]
	v_mfma_f32_16x16x32_bf16 v[16:19], v[150:153], v[194:197], v[16:19]
	v_mfma_f32_16x16x32_bf16 v[60:63], v[146:149], v[162:165], v[60:63]
	v_mfma_f32_16x16x32_bf16 v[56:59], v[154:157], v[162:165], v[56:59]
	v_mfma_f32_16x16x32_bf16 v[52:55], v[146:149], v[170:173], v[52:55]
	v_mfma_f32_16x16x32_bf16 v[48:51], v[154:157], v[170:173], v[48:51]
	v_mfma_f32_16x16x32_bf16 v[36:39], v[146:149], v[190:193], v[36:39]
	v_mfma_f32_16x16x32_bf16 v[32:35], v[154:157], v[190:193], v[32:35]
	s_waitcnt lgkmcnt(0)
	v_mfma_f32_16x16x32_bf16 v[20:23], v[146:149], v[198:201], v[20:23]
	v_mfma_f32_16x16x32_bf16 v[16:19], v[154:157], v[198:201], v[16:19]
	s_barrier
	s_add_u32 s14, s14, 0x40080
	s_addc_u32 s15, s15, 0
	s_add_i32 m0, s20, 0x1c000
	s_nop 0
	global_load_lds_dwordx4 v176, s[14:15]
	s_add_i32 m0, s20, 0x1e000
	s_nop 0
	global_load_lds_dwordx4 v128, s[14:15]
	s_waitcnt vmcnt(6)
	s_barrier
	v_mfma_f32_16x16x32_bf16 v[44:47], v[202:205], v[158:161], v[44:47]
	v_mfma_f32_16x16x32_bf16 v[40:43], v[210:213], v[158:161], v[40:43]
	v_mfma_f32_16x16x32_bf16 v[28:31], v[202:205], v[166:169], v[28:31]
	v_mfma_f32_16x16x32_bf16 v[24:27], v[210:213], v[166:169], v[24:27]
	v_mfma_f32_16x16x32_bf16 v[12:15], v[202:205], v[182:185], v[12:15]
	v_mfma_f32_16x16x32_bf16 v[8:11], v[210:213], v[182:185], v[8:11]
	v_mfma_f32_16x16x32_bf16 v[4:7], v[202:205], v[194:197], v[4:7]
	v_mfma_f32_16x16x32_bf16 v[0:3], v[210:213], v[194:197], v[0:3]
	v_mfma_f32_16x16x32_bf16 v[44:47], v[206:209], v[162:165], v[44:47]
	v_mfma_f32_16x16x32_bf16 v[40:43], v[214:217], v[162:165], v[40:43]
	v_mfma_f32_16x16x32_bf16 v[28:31], v[206:209], v[170:173], v[28:31]
	v_mfma_f32_16x16x32_bf16 v[24:27], v[214:217], v[170:173], v[24:27]
	v_mfma_f32_16x16x32_bf16 v[12:15], v[206:209], v[190:193], v[12:15]
	v_mfma_f32_16x16x32_bf16 v[8:11], v[214:217], v[190:193], v[8:11]
	v_mfma_f32_16x16x32_bf16 v[4:7], v[206:209], v[198:201], v[4:7]
	v_mfma_f32_16x16x32_bf16 v[0:3], v[214:217], v[198:201], v[0:3]
	s_add_i32 s45, s45, 2
	s_add_u32 s12, s12, 0x100
	s_addc_u32 s13, s13, 0
	s_add_u32 s43, s43, 0x100
	s_addc_u32 s44, s44, 0
	s_cmp_gt_u32 s45, 13
	s_barrier
